# lora phase rewritten by hand (exp2/rcp identities, branch-free), L2 warm-up, n-tiles split across wave pairs
# speedup vs baseline: 1.0309x; 1.0309x over previous
; #define LAS __attribute__((address_space(3)))
; __device__ __forceinline__ unsigned pk2(float lo, float hi) { f32x2 v = {lo, hi}; bf16x2_t b = __builtin_convertvector(v, bf16x2_t); return __builtin_bit_cast(unsigned, b); }
; __device__ __forceinline__ float sigmoidf_(float x) { return frcp(1.f + fexp2(-1.4426950408889634f * x)); }
;     __device__ __forceinline__ const float* in(int i) const { return (const float*)ptr(i); }
;     __device__ __forceinline__ unsigned char* ws() const { return (unsigned char*)ptr(37); }
; #define ws (p.ws())
; __device__ __forceinline__ void phase_lora(const Ctx& p, LAS unsigned char* lds) {
;     const int tid = threadIdx.x, lane = tid & 63, wave = __builtin_amdgcn_readfirstlane(tid >> 6), q = lane & 15, g = lane >> 4;
;     const bf16_t* ZRW = (const bf16_t*)(p.ws() + WS_ZRW);
;     float* DEC = (float*)(p.ws() + WS_DEC); bf16_t* AB = (bf16_t*)(p.ws() + WS_ABUF); bf16_t* GG = (bf16_t*)(p.ws() + WS_GG);
;     const bf16_t* w2T = (const bf16_t*)(p.ws() + WS_LW); const bf16_t* a2T = w2T + 512 * 64; const bf16_t* g2T = a2T + 512 * 64;
;     LAS bf16_t* X = (LAS bf16_t*)(lds + wave * 16 * 264 * 2);
;     const float* mu = p.in(17) + 1536;
;     for (int it = blockIdx.x + gridDim.x * wave; it < MR / 16; it += gridDim.x * 8) {
;         const int r0 = it * 16;
;         {
;             const int tt = lane >> 2, cq = lane & 3, row = r0 + tt;
; #pragma unroll
;             for (int j = 0; j < 8; ++j) {
;                 const int c = cq * 64 + j * 8;
;                 float m8[8], z[8];
; #pragma unroll
;                 for (int e = 0; e < 8; ++e) m8[e] = mu[c + e];
;                 zshift8(p, ZRW, row, 1536 + c, m8, z);
; #pragma unroll
;                 for (int e = 0; e < 8; ++e) z[e] = cq == 0 ? tanhf(z[e]) : (cq == 1 ? z[e] : sigmoidf_(z[e]));
;                 u32x4 w; w.x = pk2(z[0], z[1]); w.y = pk2(z[2], z[3]); w.z = pk2(z[4], z[5]); w.w = pk2(z[6], z[7]);
;                 *(LAS u32x4*)(X + tt * 264 + c) = w;
;             }
;         }
.LBB0_870:
	s_cmp_lt_i32 s36, 6
	s_cselect_b64 s[4:5], -1, 0
	s_and_b64 s[10:11], s[4:5], s[2:3]
	s_andn2_b64 vcc, exec, s[10:11]
	s_cbranch_vccnz .LBB0_1564
	s_waitcnt vmcnt(0)
	v_mov_b32_e32 v0, 0x23528
	v_mov_b32_e32 v1, 0x23488
	v_mov_b32_e32 v2, 0x23428
	v_mov_b32_e32 v3, 0x23490
	v_mov_b32_e32 v4, 0x234a0
	ds_read_b64 v[6:7], v0
	ds_read_b64 v[8:9], v1
	ds_read_b64 v[10:11], v2
	ds_read_b64 v[12:13], v3
	ds_read_b64 v[14:15], v4
	v_readfirstlane_b32 s2, v180
	s_waitcnt lgkmcnt(0)
	v_readfirstlane_b32 s12, v6
	v_readfirstlane_b32 s13, v7
	v_readfirstlane_b32 s16, v8
	v_readfirstlane_b32 s17, v9
	v_readfirstlane_b32 s18, v10
	v_readfirstlane_b32 s19, v11
	v_readfirstlane_b32 s20, v12
	v_readfirstlane_b32 s21, v13
	v_readfirstlane_b32 s22, v14
	v_readfirstlane_b32 s23, v15
	s_nop 4
	s_lshr_b32 s27, s2, 6
	s_and_b32 s2, s27, 3
	s_lshr_b32 s56, s27, 2
	s_mul_i32 s2, s2, s38
	s_add_i32 s26, s2, s28
	s_add_u32 s14, s12, 0x8340000
	s_addc_u32 s15, s13, 0
	s_add_u32 s16, s16, 0x1800
	s_addc_u32 s17, s17, 0
	s_add_u32 s24, s12, 0x3110000
	s_addc_u32 s25, s13, 0
	s_add_u32 s40, s12, 0x3120000
	s_addc_u32 s41, s13, 0
	s_add_u32 s42, s12, 0x3130000
	s_addc_u32 s43, s13, 0
	s_add_u32 s44, s12, 0x3200000
	s_addc_u32 s45, s13, 0
	s_add_u32 s46, s12, 0x4240000
	s_addc_u32 s47, s13, 0
	s_add_u32 s54, s12, 0xfd20000
	s_addc_u32 s55, s13, 0
	v_and_b32_e32 v0, 63, v180
	v_lshrrev_b32_e32 v1, 2, v0
	v_and_b32_e32 v2, 3, v0
	v_and_b32_e32 v10, 15, v0
	v_lshrrev_b32_e32 v11, 4, v0
	v_cmp_eq_u32_e32 vcc, 0, v2
	v_mov_b32_e32 v12, 0xbfb8aa3b
	v_mov_b32_e32 v13, 0x4038aa3b
	v_cndmask_b32_e32 v7, v12, v13, vcc
	v_mov_b32_e32 v12, 1.0
	v_mov_b32_e32 v13, -2.0
	v_cndmask_b32_e32 v8, v12, v13, vcc
	v_mov_b32_e32 v12, 0
	v_mov_b32_e32 v13, 1.0
	v_cndmask_b32_e32 v9, v12, v13, vcc
	v_cmp_eq_u32_e64 s[48:49], 1, v2
	s_mul_i32 s3, s27, 0x2100
	v_mul_u32_u24_e32 v6, 0x210, v1
	v_lshl_add_u32 v6, v2, 7, v6
	v_add_u32_e32 v6, s3, v6
	v_mul_u32_u24_e32 v14, 0x210, v10
	v_lshl_add_u32 v14, v11, 4, v14
	v_add_u32_e32 v14, s3, v14
	v_lshlrev_b32_e32 v5, 8, v2
	s_lshr_b32 s2, s28, 3
	s_and_b32 s2, s2, 31
	s_lshl_b32 s2, s2, 13
	v_lshlrev_b32_e32 v12, 4, v180
	v_add_u32_e32 v12, s2, v12
	v_and_b32_e32 v13, 0x7f, v180
	v_lshlrev_b32_e32 v13, 4, v13
	global_load_dwordx4 v[164:167], v12, s[24:25]
	global_load_dwordx4 v[168:171], v13, s[20:21]
	global_load_dwordx4 v[172:175], v13, s[22:23]
.Llora_item:
	s_cmpk_gt_i32 s26, 0x407
	s_cbranch_scc1 .Llora_done
	s_and_b32 s2, s26, 0xff
	s_cmp_eq_u32 s2, 0
	s_cselect_b32 s52, 1, 0
	s_cmpk_gt_i32 s26, 0x3ff
	s_cselect_b32 s53, 1, 0
	s_or_b32 s52, s52, s53
	s_lshl_b32 s2, s26, 4
	v_add_u32_e32 v3, s2, v1
	v_mul_u32_u24_e32 v3, 0xe00, v3
	v_lshl_add_u32 v3, v2, 7, v3
	v_add_u32_e32 v3, 0xc00, v3
	v_subrev_u32_e32 v4, 0xe00, v3
	v_cmp_gt_u32_e32 vcc, 0xe00, v3
	s_nop 1
	v_cndmask_b32_e32 v4, v4, v3, vcc
	global_load_dwordx4 v[16:19], v3, s[14:15] offset:0
	global_load_dwordx4 v[20:23], v3, s[14:15] offset:16
	global_load_dwordx4 v[24:27], v3, s[14:15] offset:32
	global_load_dwordx4 v[28:31], v3, s[14:15] offset:48
	global_load_dwordx4 v[32:35], v3, s[14:15] offset:64
	global_load_dwordx4 v[36:39], v3, s[14:15] offset:80
	global_load_dwordx4 v[40:43], v3, s[14:15] offset:96
	global_load_dwordx4 v[44:47], v3, s[14:15] offset:112
	global_load_dwordx4 v[48:51], v4, s[14:15] offset:0
	global_load_dwordx4 v[52:55], v4, s[14:15] offset:16
	global_load_dwordx4 v[56:59], v4, s[14:15] offset:32
	global_load_dwordx4 v[60:63], v4, s[14:15] offset:48
	global_load_dwordx4 v[64:67], v4, s[14:15] offset:64
	global_load_dwordx4 v[68:71], v4, s[14:15] offset:80
	global_load_dwordx4 v[72:75], v4, s[14:15] offset:96
	global_load_dwordx4 v[76:79], v4, s[14:15] offset:112
	global_load_dwordx4 v[80:83], v5, s[16:17] offset:0
	global_load_dwordx4 v[84:87], v5, s[16:17] offset:16
	global_load_dwordx4 v[88:91], v5, s[16:17] offset:32
	global_load_dwordx4 v[92:95], v5, s[16:17] offset:48
	global_load_dwordx4 v[96:99], v5, s[16:17] offset:64
	global_load_dwordx4 v[100:103], v5, s[16:17] offset:80
	global_load_dwordx4 v[104:107], v5, s[16:17] offset:96
	global_load_dwordx4 v[108:111], v5, s[16:17] offset:112
	global_load_dwordx4 v[112:115], v5, s[16:17] offset:128
	global_load_dwordx4 v[116:119], v5, s[16:17] offset:144
	global_load_dwordx4 v[120:123], v5, s[16:17] offset:160
	global_load_dwordx4 v[124:127], v5, s[16:17] offset:176
	global_load_dwordx4 v[128:131], v5, s[16:17] offset:192
	global_load_dwordx4 v[132:135], v5, s[16:17] offset:208
	global_load_dwordx4 v[136:139], v5, s[16:17] offset:224
	global_load_dwordx4 v[140:143], v5, s[16:17] offset:240
	s_sub_i32 s2, s26, 0x400
	s_mul_i32 s2, s2, 0x1c00
	s_add_i32 s2, s2, 0x1800
	v_add_u32_e32 v15, s2, v5
	s_waitcnt vmcnt(0)
	v_lshlrev_b32_e32 v144, 16, v16
	v_and_b32_e32 v145, 0xffff0000, v16
	v_lshlrev_b32_e32 v152, 16, v48
	v_and_b32_e32 v153, 0xffff0000, v48
	v_lshlrev_b32_e32 v146, 16, v17
	v_and_b32_e32 v147, 0xffff0000, v17
	v_lshlrev_b32_e32 v154, 16, v49
	v_and_b32_e32 v155, 0xffff0000, v49
	v_lshlrev_b32_e32 v148, 16, v18
	v_and_b32_e32 v149, 0xffff0000, v18
	v_lshlrev_b32_e32 v156, 16, v50
	v_and_b32_e32 v157, 0xffff0000, v50
	v_lshlrev_b32_e32 v150, 16, v19
	v_and_b32_e32 v151, 0xffff0000, v19
	v_lshlrev_b32_e32 v158, 16, v51
	v_and_b32_e32 v159, 0xffff0000, v51
	s_cmp_eq_u32 s52, 0
	s_cbranch_scc1 .Llora_nf0
	s_mov_b64 s[50:51], exec
	s_mov_b64 exec, 15
	s_cmp_eq_u32 s53, 0
	s_cbranch_scc1 .Llora_pz0
	global_load_dwordx4 v[152:155], v15, s[18:19] offset:0
	global_load_dwordx4 v[156:159], v15, s[18:19] offset:16
	s_waitcnt vmcnt(0)
	s_branch .Llora_pe0
; #define LAS __attribute__((address_space(3)))
; __device__ __forceinline__ unsigned pk2(float lo, float hi) { f32x2 v = {lo, hi}; bf16x2_t b = __builtin_convertvector(v, bf16x2_t); return __builtin_bit_cast(unsigned, b); }
; __device__ __forceinline__ float sigmoidf_(float x) { return frcp(1.f + fexp2(-1.4426950408889634f * x)); }
;     __device__ __forceinline__ const float* in(int i) const { return (const float*)ptr(i); }
; __device__ __forceinline__ void unpack8(const u32x4 w, float (&f)[8]) { f[0] = bflo(w.x); f[1] = bfhi(w.x); f[2] = bflo(w.y); f[3] = bfhi(w.y); f[4] = bflo(w.z); f[5] = bfhi(w.z); f[6] = bflo(w.w); f[7] = bfhi(w.w); }
; __device__ __forceinline__ void zshift8(const Ctx& p, const bf16_t* ZRW, int row, int c, const float (&mu)[8], float (&o)[8]) {
;     float z[8], pv[8];
;     unpack8(*(const u32x4*)(ZRW + (size_t)row * SHW + c), z);
;     bool first; int bsmp = 0;
;     if (row < MPR) first = (row & (TP - 1)) == 0; else { first = ((row - MPR) & 15) == 0; bsmp = (row - MPR) >> 4; }
;     if (!first) unpack8(*(const u32x4*)(ZRW + (size_t)(row - 1) * SHW + c), pv);
;     else if (row < MPR) {
; #pragma unroll
;         for (int e = 0; e < 8; ++e) pv[e] = 0.f;
;     } else { const float* s0 = p.in(5) + (size_t)bsmp * SHW + c;
; #pragma unroll
;         for (int e = 0; e < 8; ++e) pv[e] = s0[e]; }
; #pragma unroll
;     for (int e = 0; e < 8; ++e) o[e] = z[e] + (pv[e] - z[e]) * mu[e];
; __device__ __forceinline__ void phase_lora(const Ctx& p, LAS unsigned char* lds) {
;     ...
;             const int tt = lane >> 2, cq = lane & 3, row = r0 + tt;
; #pragma unroll
;             for (int j = 0; j < 8; ++j) {
;                 const int c = cq * 64 + j * 8;
;                 float m8[8], z[8];
; #pragma unroll
;                 for (int e = 0; e < 8; ++e) m8[e] = mu[c + e];
;                 zshift8(p, ZRW, row, 1536 + c, m8, z);
; #pragma unroll
;                 for (int e = 0; e < 8; ++e) z[e] = cq == 0 ? tanhf(z[e]) : (cq == 1 ? z[e] : sigmoidf_(z[e]));
;                 u32x4 w; w.x = pk2(z[0], z[1]); w.y = pk2(z[2], z[3]); w.z = pk2(z[4], z[5]); w.w = pk2(z[6], z[7]);
;                 *(LAS u32x4*)(X + tt * 264 + c) = w;
;             }
.Llora_pz0:
	v_mov_b32_e32 v152, 0
	v_mov_b32_e32 v153, 0
	v_mov_b32_e32 v154, 0
	v_mov_b32_e32 v155, 0
	v_mov_b32_e32 v156, 0
	v_mov_b32_e32 v157, 0
	v_mov_b32_e32 v158, 0
	v_mov_b32_e32 v159, 0
.Llora_pe0:
	s_mov_b64 exec, s[50:51]
.Llora_nf0:
	v_sub_f32_e32 v152, v152, v144
	v_sub_f32_e32 v153, v153, v145
	v_sub_f32_e32 v154, v154, v146
	v_sub_f32_e32 v155, v155, v147
	v_sub_f32_e32 v156, v156, v148
	v_sub_f32_e32 v157, v157, v149
	v_sub_f32_e32 v158, v158, v150
	v_sub_f32_e32 v159, v159, v151
	v_fmac_f32_e32 v144, v152, v80
	v_fmac_f32_e32 v145, v153, v81
	v_fmac_f32_e32 v146, v154, v82
	v_fmac_f32_e32 v147, v155, v83
	v_fmac_f32_e32 v148, v156, v84
	v_fmac_f32_e32 v149, v157, v85
	v_fmac_f32_e32 v150, v158, v86
	v_fmac_f32_e32 v151, v159, v87
	v_mul_f32_e32 v152, v7, v144
	v_mul_f32_e32 v153, v7, v145
	v_mul_f32_e32 v154, v7, v146
	v_mul_f32_e32 v155, v7, v147
	v_mul_f32_e32 v156, v7, v148
	v_mul_f32_e32 v157, v7, v149
	v_mul_f32_e32 v158, v7, v150
	v_mul_f32_e32 v159, v7, v151
	v_exp_f32_e32 v152, v152
	v_exp_f32_e32 v153, v153
	v_exp_f32_e32 v154, v154
	v_exp_f32_e32 v155, v155
	v_exp_f32_e32 v156, v156
	v_exp_f32_e32 v157, v157
	v_exp_f32_e32 v158, v158
	v_exp_f32_e32 v159, v159
	v_add_f32_e32 v152, 1.0, v152
	v_add_f32_e32 v153, 1.0, v153
	v_add_f32_e32 v154, 1.0, v154
	v_add_f32_e32 v155, 1.0, v155
	v_add_f32_e32 v156, 1.0, v156
	v_add_f32_e32 v157, 1.0, v157
	v_add_f32_e32 v158, 1.0, v158
	v_add_f32_e32 v159, 1.0, v159
	v_rcp_f32_e32 v152, v152
	v_rcp_f32_e32 v153, v153
	v_rcp_f32_e32 v154, v154
	v_rcp_f32_e32 v155, v155
	v_rcp_f32_e32 v156, v156
	v_rcp_f32_e32 v157, v157
	v_rcp_f32_e32 v158, v158
	v_rcp_f32_e32 v159, v159
	v_fma_f32 v152, v152, v8, v9
	v_fma_f32 v153, v153, v8, v9
	v_fma_f32 v154, v154, v8, v9
	v_fma_f32 v155, v155, v8, v9
	v_fma_f32 v156, v156, v8, v9
	v_fma_f32 v157, v157, v8, v9
	v_fma_f32 v158, v158, v8, v9
	v_fma_f32 v159, v159, v8, v9
	v_cndmask_b32_e64 v152, v152, v144, s[48:49]
	v_cndmask_b32_e64 v153, v153, v145, s[48:49]
	v_cndmask_b32_e64 v154, v154, v146, s[48:49]
	v_cndmask_b32_e64 v155, v155, v147, s[48:49]
	v_cndmask_b32_e64 v156, v156, v148, s[48:49]
	v_cndmask_b32_e64 v157, v157, v149, s[48:49]
	v_cndmask_b32_e64 v158, v158, v150, s[48:49]
	v_cndmask_b32_e64 v159, v159, v151, s[48:49]
	v_cvt_pk_bf16_f32 v160, v152, v153
	v_cvt_pk_bf16_f32 v161, v154, v155
	v_cvt_pk_bf16_f32 v162, v156, v157
	v_cvt_pk_bf16_f32 v163, v158, v159
	ds_write_b128 v6, v[160:163] offset:0
	v_lshlrev_b32_e32 v144, 16, v20
	v_and_b32_e32 v145, 0xffff0000, v20
	v_lshlrev_b32_e32 v152, 16, v52
	v_and_b32_e32 v153, 0xffff0000, v52
	v_lshlrev_b32_e32 v146, 16, v21
	v_and_b32_e32 v147, 0xffff0000, v21
	v_lshlrev_b32_e32 v154, 16, v53
	v_and_b32_e32 v155, 0xffff0000, v53
	v_lshlrev_b32_e32 v148, 16, v22
	v_and_b32_e32 v149, 0xffff0000, v22
	v_lshlrev_b32_e32 v156, 16, v54
	v_and_b32_e32 v157, 0xffff0000, v54
	v_lshlrev_b32_e32 v150, 16, v23
	v_and_b32_e32 v151, 0xffff0000, v23
	v_lshlrev_b32_e32 v158, 16, v55
	v_and_b32_e32 v159, 0xffff0000, v55
	s_cmp_eq_u32 s52, 0
	s_cbranch_scc1 .Llora_nf1
	s_mov_b64 s[50:51], exec
	s_mov_b64 exec, 15
	s_cmp_eq_u32 s53, 0
	s_cbranch_scc1 .Llora_pz1
	global_load_dwordx4 v[152:155], v15, s[18:19] offset:32
	global_load_dwordx4 v[156:159], v15, s[18:19] offset:48
	s_waitcnt vmcnt(0)
	s_branch .Llora_pe1

; #define LAS __attribute__((address_space(3)))
; __device__ __forceinline__ unsigned pk2(float lo, float hi) { f32x2 v = {lo, hi}; bf16x2_t b = __builtin_convertvector(v, bf16x2_t); return __builtin_bit_cast(unsigned, b); }
; __device__ __forceinline__ float sigmoidf_(float x) { return frcp(1.f + fexp2(-1.4426950408889634f * x)); }
;     __device__ __forceinline__ const float* in(int i) const { return (const float*)ptr(i); }
; __device__ __forceinline__ void unpack8(const u32x4 w, float (&f)[8]) { f[0] = bflo(w.x); f[1] = bfhi(w.x); f[2] = bflo(w.y); f[3] = bfhi(w.y); f[4] = bflo(w.z); f[5] = bfhi(w.z); f[6] = bflo(w.w); f[7] = bfhi(w.w); }
; __device__ __forceinline__ void zshift8(const Ctx& p, const bf16_t* ZRW, int row, int c, const float (&mu)[8], float (&o)[8]) {
;     float z[8], pv[8];
;     unpack8(*(const u32x4*)(ZRW + (size_t)row * SHW + c), z);
;     bool first; int bsmp = 0;
;     if (row < MPR) first = (row & (TP - 1)) == 0; else { first = ((row - MPR) & 15) == 0; bsmp = (row - MPR) >> 4; }
;     if (!first) unpack8(*(const u32x4*)(ZRW + (size_t)(row - 1) * SHW + c), pv);
;     else if (row < MPR) {
; #pragma unroll
;         for (int e = 0; e < 8; ++e) pv[e] = 0.f;
;     } else { const float* s0 = p.in(5) + (size_t)bsmp * SHW + c;
; #pragma unroll
;         for (int e = 0; e < 8; ++e) pv[e] = s0[e]; }
; #pragma unroll
;     for (int e = 0; e < 8; ++e) o[e] = z[e] + (pv[e] - z[e]) * mu[e];
; __device__ __forceinline__ void phase_lora(const Ctx& p, LAS unsigned char* lds) {
;     ...
;             const int tt = lane >> 2, cq = lane & 3, row = r0 + tt;
; #pragma unroll
;             for (int j = 0; j < 8; ++j) {
;                 const int c = cq * 64 + j * 8;
;                 float m8[8], z[8];
; #pragma unroll
;                 for (int e = 0; e < 8; ++e) m8[e] = mu[c + e];
;                 zshift8(p, ZRW, row, 1536 + c, m8, z);
; #pragma unroll
;                 for (int e = 0; e < 8; ++e) z[e] = cq == 0 ? tanhf(z[e]) : (cq == 1 ? z[e] : sigmoidf_(z[e]));
;                 u32x4 w; w.x = pk2(z[0], z[1]); w.y = pk2(z[2], z[3]); w.z = pk2(z[4], z[5]); w.w = pk2(z[6], z[7]);
;                 *(LAS u32x4*)(X + tt * 264 + c) = w;
;             }
.Llora_nf1:
	v_sub_f32_e32 v152, v152, v144
	v_sub_f32_e32 v153, v153, v145
	v_sub_f32_e32 v154, v154, v146
	v_sub_f32_e32 v155, v155, v147
	v_sub_f32_e32 v156, v156, v148
	v_sub_f32_e32 v157, v157, v149
	v_sub_f32_e32 v158, v158, v150
	v_sub_f32_e32 v159, v159, v151
	v_fmac_f32_e32 v144, v152, v88
	v_fmac_f32_e32 v145, v153, v89
	v_fmac_f32_e32 v146, v154, v90
	v_fmac_f32_e32 v147, v155, v91
	v_fmac_f32_e32 v148, v156, v92
	v_fmac_f32_e32 v149, v157, v93
	v_fmac_f32_e32 v150, v158, v94
	v_fmac_f32_e32 v151, v159, v95
	v_mul_f32_e32 v152, v7, v144
	v_mul_f32_e32 v153, v7, v145
	v_mul_f32_e32 v154, v7, v146
	v_mul_f32_e32 v155, v7, v147
	v_mul_f32_e32 v156, v7, v148
	v_mul_f32_e32 v157, v7, v149
	v_mul_f32_e32 v158, v7, v150
	v_mul_f32_e32 v159, v7, v151
	v_exp_f32_e32 v152, v152
	v_exp_f32_e32 v153, v153
	v_exp_f32_e32 v154, v154
	v_exp_f32_e32 v155, v155
	v_exp_f32_e32 v156, v156
	v_exp_f32_e32 v157, v157
	v_exp_f32_e32 v158, v158
	v_exp_f32_e32 v159, v159
	v_add_f32_e32 v152, 1.0, v152
	v_add_f32_e32 v153, 1.0, v153
	v_add_f32_e32 v154, 1.0, v154
	v_add_f32_e32 v155, 1.0, v155
	v_add_f32_e32 v156, 1.0, v156
	v_add_f32_e32 v157, 1.0, v157
	v_add_f32_e32 v158, 1.0, v158
	v_add_f32_e32 v159, 1.0, v159
	v_rcp_f32_e32 v152, v152
	v_rcp_f32_e32 v153, v153
	v_rcp_f32_e32 v154, v154
	v_rcp_f32_e32 v155, v155
	v_rcp_f32_e32 v156, v156
	v_rcp_f32_e32 v157, v157
	v_rcp_f32_e32 v158, v158
	v_rcp_f32_e32 v159, v159
	v_fma_f32 v152, v152, v8, v9
	v_fma_f32 v153, v153, v8, v9
	v_fma_f32 v154, v154, v8, v9
	v_fma_f32 v155, v155, v8, v9
	v_fma_f32 v156, v156, v8, v9
	v_fma_f32 v157, v157, v8, v9
	v_fma_f32 v158, v158, v8, v9
	v_fma_f32 v159, v159, v8, v9
	v_cndmask_b32_e64 v152, v152, v144, s[48:49]
	v_cndmask_b32_e64 v153, v153, v145, s[48:49]
	v_cndmask_b32_e64 v154, v154, v146, s[48:49]
	v_cndmask_b32_e64 v155, v155, v147, s[48:49]
	v_cndmask_b32_e64 v156, v156, v148, s[48:49]
	v_cndmask_b32_e64 v157, v157, v149, s[48:49]
	v_cndmask_b32_e64 v158, v158, v150, s[48:49]
	v_cndmask_b32_e64 v159, v159, v151, s[48:49]
	v_cvt_pk_bf16_f32 v160, v152, v153
	v_cvt_pk_bf16_f32 v161, v154, v155
	v_cvt_pk_bf16_f32 v162, v156, v157
	v_cvt_pk_bf16_f32 v163, v158, v159
	ds_write_b128 v6, v[160:163] offset:16
	v_lshlrev_b32_e32 v144, 16, v24
	v_and_b32_e32 v145, 0xffff0000, v24
	v_lshlrev_b32_e32 v152, 16, v56
	v_and_b32_e32 v153, 0xffff0000, v56
	v_lshlrev_b32_e32 v146, 16, v25
	v_and_b32_e32 v147, 0xffff0000, v25
	v_lshlrev_b32_e32 v154, 16, v57
	v_and_b32_e32 v155, 0xffff0000, v57
	v_lshlrev_b32_e32 v148, 16, v26
	v_and_b32_e32 v149, 0xffff0000, v26
	v_lshlrev_b32_e32 v156, 16, v58
	v_and_b32_e32 v157, 0xffff0000, v58
	v_lshlrev_b32_e32 v150, 16, v27
	v_and_b32_e32 v151, 0xffff0000, v27
	v_lshlrev_b32_e32 v158, 16, v59
	v_and_b32_e32 v159, 0xffff0000, v59
	s_cmp_eq_u32 s52, 0
	s_cbranch_scc1 .Llora_nf2
	s_mov_b64 s[50:51], exec
	s_mov_b64 exec, 15
	s_cmp_eq_u32 s53, 0
	s_cbranch_scc1 .Llora_pz2
	global_load_dwordx4 v[152:155], v15, s[18:19] offset:64
	global_load_dwordx4 v[156:159], v15, s[18:19] offset:80
	s_waitcnt vmcnt(0)
	s_branch .Llora_pe2

; #define LAS __attribute__((address_space(3)))
; __device__ __forceinline__ unsigned pk2(float lo, float hi) { f32x2 v = {lo, hi}; bf16x2_t b = __builtin_convertvector(v, bf16x2_t); return __builtin_bit_cast(unsigned, b); }
; __device__ __forceinline__ float sigmoidf_(float x) { return frcp(1.f + fexp2(-1.4426950408889634f * x)); }
;     __device__ __forceinline__ const float* in(int i) const { return (const float*)ptr(i); }
; __device__ __forceinline__ void unpack8(const u32x4 w, float (&f)[8]) { f[0] = bflo(w.x); f[1] = bfhi(w.x); f[2] = bflo(w.y); f[3] = bfhi(w.y); f[4] = bflo(w.z); f[5] = bfhi(w.z); f[6] = bflo(w.w); f[7] = bfhi(w.w); }
; __device__ __forceinline__ void zshift8(const Ctx& p, const bf16_t* ZRW, int row, int c, const float (&mu)[8], float (&o)[8]) {
;     float z[8], pv[8];
;     unpack8(*(const u32x4*)(ZRW + (size_t)row * SHW + c), z);
;     bool first; int bsmp = 0;
;     if (row < MPR) first = (row & (TP - 1)) == 0; else { first = ((row - MPR) & 15) == 0; bsmp = (row - MPR) >> 4; }
;     if (!first) unpack8(*(const u32x4*)(ZRW + (size_t)(row - 1) * SHW + c), pv);
;     else if (row < MPR) {
; #pragma unroll
;         for (int e = 0; e < 8; ++e) pv[e] = 0.f;
;     } else { const float* s0 = p.in(5) + (size_t)bsmp * SHW + c;
; #pragma unroll
;         for (int e = 0; e < 8; ++e) pv[e] = s0[e]; }
; #pragma unroll
;     for (int e = 0; e < 8; ++e) o[e] = z[e] + (pv[e] - z[e]) * mu[e];
; __device__ __forceinline__ void phase_lora(const Ctx& p, LAS unsigned char* lds) {
;     ...
;             const int tt = lane >> 2, cq = lane & 3, row = r0 + tt;
; #pragma unroll
;             for (int j = 0; j < 8; ++j) {
;                 const int c = cq * 64 + j * 8;
;                 float m8[8], z[8];
; #pragma unroll
;                 for (int e = 0; e < 8; ++e) m8[e] = mu[c + e];
;                 zshift8(p, ZRW, row, 1536 + c, m8, z);
; #pragma unroll
;                 for (int e = 0; e < 8; ++e) z[e] = cq == 0 ? tanhf(z[e]) : (cq == 1 ? z[e] : sigmoidf_(z[e]));
;                 u32x4 w; w.x = pk2(z[0], z[1]); w.y = pk2(z[2], z[3]); w.z = pk2(z[4], z[5]); w.w = pk2(z[6], z[7]);
;                 *(LAS u32x4*)(X + tt * 264 + c) = w;
;             }
.Llora_nf2:
	v_sub_f32_e32 v152, v152, v144
	v_sub_f32_e32 v153, v153, v145
	v_sub_f32_e32 v154, v154, v146
	v_sub_f32_e32 v155, v155, v147
	v_sub_f32_e32 v156, v156, v148
	v_sub_f32_e32 v157, v157, v149
	v_sub_f32_e32 v158, v158, v150
	v_sub_f32_e32 v159, v159, v151
	v_fmac_f32_e32 v144, v152, v96
	v_fmac_f32_e32 v145, v153, v97
	v_fmac_f32_e32 v146, v154, v98
	v_fmac_f32_e32 v147, v155, v99
	v_fmac_f32_e32 v148, v156, v100
	v_fmac_f32_e32 v149, v157, v101
	v_fmac_f32_e32 v150, v158, v102
	v_fmac_f32_e32 v151, v159, v103
	v_mul_f32_e32 v152, v7, v144
	v_mul_f32_e32 v153, v7, v145
	v_mul_f32_e32 v154, v7, v146
	v_mul_f32_e32 v155, v7, v147
	v_mul_f32_e32 v156, v7, v148
	v_mul_f32_e32 v157, v7, v149
	v_mul_f32_e32 v158, v7, v150
	v_mul_f32_e32 v159, v7, v151
	v_exp_f32_e32 v152, v152
	v_exp_f32_e32 v153, v153
	v_exp_f32_e32 v154, v154
	v_exp_f32_e32 v155, v155
	v_exp_f32_e32 v156, v156
	v_exp_f32_e32 v157, v157
	v_exp_f32_e32 v158, v158
	v_exp_f32_e32 v159, v159
	v_add_f32_e32 v152, 1.0, v152
	v_add_f32_e32 v153, 1.0, v153
	v_add_f32_e32 v154, 1.0, v154
	v_add_f32_e32 v155, 1.0, v155
	v_add_f32_e32 v156, 1.0, v156
	v_add_f32_e32 v157, 1.0, v157
	v_add_f32_e32 v158, 1.0, v158
	v_add_f32_e32 v159, 1.0, v159
	v_rcp_f32_e32 v152, v152
	v_rcp_f32_e32 v153, v153
	v_rcp_f32_e32 v154, v154
	v_rcp_f32_e32 v155, v155
	v_rcp_f32_e32 v156, v156
	v_rcp_f32_e32 v157, v157
	v_rcp_f32_e32 v158, v158
	v_rcp_f32_e32 v159, v159
	v_fma_f32 v152, v152, v8, v9
	v_fma_f32 v153, v153, v8, v9
	v_fma_f32 v154, v154, v8, v9
	v_fma_f32 v155, v155, v8, v9
	v_fma_f32 v156, v156, v8, v9
	v_fma_f32 v157, v157, v8, v9
	v_fma_f32 v158, v158, v8, v9
	v_fma_f32 v159, v159, v8, v9
	v_cndmask_b32_e64 v152, v152, v144, s[48:49]
	v_cndmask_b32_e64 v153, v153, v145, s[48:49]
	v_cndmask_b32_e64 v154, v154, v146, s[48:49]
	v_cndmask_b32_e64 v155, v155, v147, s[48:49]
	v_cndmask_b32_e64 v156, v156, v148, s[48:49]
	v_cndmask_b32_e64 v157, v157, v149, s[48:49]
	v_cndmask_b32_e64 v158, v158, v150, s[48:49]
	v_cndmask_b32_e64 v159, v159, v151, s[48:49]
	v_cvt_pk_bf16_f32 v160, v152, v153
	v_cvt_pk_bf16_f32 v161, v154, v155
	v_cvt_pk_bf16_f32 v162, v156, v157
	v_cvt_pk_bf16_f32 v163, v158, v159
	ds_write_b128 v6, v[160:163] offset:32
	v_lshlrev_b32_e32 v144, 16, v28
	v_and_b32_e32 v145, 0xffff0000, v28
	v_lshlrev_b32_e32 v152, 16, v60
	v_and_b32_e32 v153, 0xffff0000, v60
	v_lshlrev_b32_e32 v146, 16, v29
	v_and_b32_e32 v147, 0xffff0000, v29
	v_lshlrev_b32_e32 v154, 16, v61
	v_and_b32_e32 v155, 0xffff0000, v61
	v_lshlrev_b32_e32 v148, 16, v30
	v_and_b32_e32 v149, 0xffff0000, v30
	v_lshlrev_b32_e32 v156, 16, v62
	v_and_b32_e32 v157, 0xffff0000, v62
	v_lshlrev_b32_e32 v150, 16, v31
	v_and_b32_e32 v151, 0xffff0000, v31
	v_lshlrev_b32_e32 v158, 16, v63
	v_and_b32_e32 v159, 0xffff0000, v63
	s_cmp_eq_u32 s52, 0
	s_cbranch_scc1 .Llora_nf3
	s_mov_b64 s[50:51], exec
	s_mov_b64 exec, 15
	s_cmp_eq_u32 s53, 0
	s_cbranch_scc1 .Llora_pz3
	global_load_dwordx4 v[152:155], v15, s[18:19] offset:96
	global_load_dwordx4 v[156:159], v15, s[18:19] offset:112
	s_waitcnt vmcnt(0)
	s_branch .Llora_pe3

; #define LAS __attribute__((address_space(3)))
; __device__ __forceinline__ unsigned pk2(float lo, float hi) { f32x2 v = {lo, hi}; bf16x2_t b = __builtin_convertvector(v, bf16x2_t); return __builtin_bit_cast(unsigned, b); }
; __device__ __forceinline__ float sigmoidf_(float x) { return frcp(1.f + fexp2(-1.4426950408889634f * x)); }
;     __device__ __forceinline__ const float* in(int i) const { return (const float*)ptr(i); }
; __device__ __forceinline__ void unpack8(const u32x4 w, float (&f)[8]) { f[0] = bflo(w.x); f[1] = bfhi(w.x); f[2] = bflo(w.y); f[3] = bfhi(w.y); f[4] = bflo(w.z); f[5] = bfhi(w.z); f[6] = bflo(w.w); f[7] = bfhi(w.w); }
; __device__ __forceinline__ void zshift8(const Ctx& p, const bf16_t* ZRW, int row, int c, const float (&mu)[8], float (&o)[8]) {
;     float z[8], pv[8];
;     unpack8(*(const u32x4*)(ZRW + (size_t)row * SHW + c), z);
;     bool first; int bsmp = 0;
;     if (row < MPR) first = (row & (TP - 1)) == 0; else { first = ((row - MPR) & 15) == 0; bsmp = (row - MPR) >> 4; }
;     if (!first) unpack8(*(const u32x4*)(ZRW + (size_t)(row - 1) * SHW + c), pv);
;     else if (row < MPR) {
; #pragma unroll
;         for (int e = 0; e < 8; ++e) pv[e] = 0.f;
;     } else { const float* s0 = p.in(5) + (size_t)bsmp * SHW + c;
; #pragma unroll
;         for (int e = 0; e < 8; ++e) pv[e] = s0[e]; }
; #pragma unroll
;     for (int e = 0; e < 8; ++e) o[e] = z[e] + (pv[e] - z[e]) * mu[e];
; __device__ __forceinline__ void phase_lora(const Ctx& p, LAS unsigned char* lds) {
;     ...
;             const int tt = lane >> 2, cq = lane & 3, row = r0 + tt;
; #pragma unroll
;             for (int j = 0; j < 8; ++j) {
;                 const int c = cq * 64 + j * 8;
;                 float m8[8], z[8];
; #pragma unroll
;                 for (int e = 0; e < 8; ++e) m8[e] = mu[c + e];
;                 zshift8(p, ZRW, row, 1536 + c, m8, z);
; #pragma unroll
;                 for (int e = 0; e < 8; ++e) z[e] = cq == 0 ? tanhf(z[e]) : (cq == 1 ? z[e] : sigmoidf_(z[e]));
;                 u32x4 w; w.x = pk2(z[0], z[1]); w.y = pk2(z[2], z[3]); w.z = pk2(z[4], z[5]); w.w = pk2(z[6], z[7]);
;                 *(LAS u32x4*)(X + tt * 264 + c) = w;
;             }
.Llora_nf3:
	v_sub_f32_e32 v152, v152, v144
	v_sub_f32_e32 v153, v153, v145
	v_sub_f32_e32 v154, v154, v146
	v_sub_f32_e32 v155, v155, v147
	v_sub_f32_e32 v156, v156, v148
	v_sub_f32_e32 v157, v157, v149
	v_sub_f32_e32 v158, v158, v150
	v_sub_f32_e32 v159, v159, v151
	v_fmac_f32_e32 v144, v152, v104
	v_fmac_f32_e32 v145, v153, v105
	v_fmac_f32_e32 v146, v154, v106
	v_fmac_f32_e32 v147, v155, v107
	v_fmac_f32_e32 v148, v156, v108
	v_fmac_f32_e32 v149, v157, v109
	v_fmac_f32_e32 v150, v158, v110
	v_fmac_f32_e32 v151, v159, v111
	v_mul_f32_e32 v152, v7, v144
	v_mul_f32_e32 v153, v7, v145
	v_mul_f32_e32 v154, v7, v146
	v_mul_f32_e32 v155, v7, v147
	v_mul_f32_e32 v156, v7, v148
	v_mul_f32_e32 v157, v7, v149
	v_mul_f32_e32 v158, v7, v150
	v_mul_f32_e32 v159, v7, v151
	v_exp_f32_e32 v152, v152
	v_exp_f32_e32 v153, v153
	v_exp_f32_e32 v154, v154
	v_exp_f32_e32 v155, v155
	v_exp_f32_e32 v156, v156
	v_exp_f32_e32 v157, v157
	v_exp_f32_e32 v158, v158
	v_exp_f32_e32 v159, v159
	v_add_f32_e32 v152, 1.0, v152
	v_add_f32_e32 v153, 1.0, v153
	v_add_f32_e32 v154, 1.0, v154
	v_add_f32_e32 v155, 1.0, v155
	v_add_f32_e32 v156, 1.0, v156
	v_add_f32_e32 v157, 1.0, v157
	v_add_f32_e32 v158, 1.0, v158
	v_add_f32_e32 v159, 1.0, v159
	v_rcp_f32_e32 v152, v152
	v_rcp_f32_e32 v153, v153
	v_rcp_f32_e32 v154, v154
	v_rcp_f32_e32 v155, v155
	v_rcp_f32_e32 v156, v156
	v_rcp_f32_e32 v157, v157
	v_rcp_f32_e32 v158, v158
	v_rcp_f32_e32 v159, v159
	v_fma_f32 v152, v152, v8, v9
	v_fma_f32 v153, v153, v8, v9
	v_fma_f32 v154, v154, v8, v9
	v_fma_f32 v155, v155, v8, v9
	v_fma_f32 v156, v156, v8, v9
	v_fma_f32 v157, v157, v8, v9
	v_fma_f32 v158, v158, v8, v9
	v_fma_f32 v159, v159, v8, v9
	v_cndmask_b32_e64 v152, v152, v144, s[48:49]
	v_cndmask_b32_e64 v153, v153, v145, s[48:49]
	v_cndmask_b32_e64 v154, v154, v146, s[48:49]
	v_cndmask_b32_e64 v155, v155, v147, s[48:49]
	v_cndmask_b32_e64 v156, v156, v148, s[48:49]
	v_cndmask_b32_e64 v157, v157, v149, s[48:49]
	v_cndmask_b32_e64 v158, v158, v150, s[48:49]
	v_cndmask_b32_e64 v159, v159, v151, s[48:49]
	v_cvt_pk_bf16_f32 v160, v152, v153
	v_cvt_pk_bf16_f32 v161, v154, v155
	v_cvt_pk_bf16_f32 v162, v156, v157
	v_cvt_pk_bf16_f32 v163, v158, v159
	ds_write_b128 v6, v[160:163] offset:48
	v_lshlrev_b32_e32 v144, 16, v32
	v_and_b32_e32 v145, 0xffff0000, v32
	v_lshlrev_b32_e32 v152, 16, v64
	v_and_b32_e32 v153, 0xffff0000, v64
	v_lshlrev_b32_e32 v146, 16, v33
	v_and_b32_e32 v147, 0xffff0000, v33
	v_lshlrev_b32_e32 v154, 16, v65
	v_and_b32_e32 v155, 0xffff0000, v65
	v_lshlrev_b32_e32 v148, 16, v34
	v_and_b32_e32 v149, 0xffff0000, v34
	v_lshlrev_b32_e32 v156, 16, v66
	v_and_b32_e32 v157, 0xffff0000, v66
	v_lshlrev_b32_e32 v150, 16, v35
	v_and_b32_e32 v151, 0xffff0000, v35
	v_lshlrev_b32_e32 v158, 16, v67
	v_and_b32_e32 v159, 0xffff0000, v67
	s_cmp_eq_u32 s52, 0
	s_cbranch_scc1 .Llora_nf4
	s_mov_b64 s[50:51], exec
	s_mov_b64 exec, 15
	s_cmp_eq_u32 s53, 0
	s_cbranch_scc1 .Llora_pz4
	global_load_dwordx4 v[152:155], v15, s[18:19] offset:128
	global_load_dwordx4 v[156:159], v15, s[18:19] offset:144
	s_waitcnt vmcnt(0)
	s_branch .Llora_pe4

; #define LAS __attribute__((address_space(3)))
; __device__ __forceinline__ unsigned pk2(float lo, float hi) { f32x2 v = {lo, hi}; bf16x2_t b = __builtin_convertvector(v, bf16x2_t); return __builtin_bit_cast(unsigned, b); }
; __device__ __forceinline__ float sigmoidf_(float x) { return frcp(1.f + fexp2(-1.4426950408889634f * x)); }
;     __device__ __forceinline__ const float* in(int i) const { return (const float*)ptr(i); }
; __device__ __forceinline__ void unpack8(const u32x4 w, float (&f)[8]) { f[0] = bflo(w.x); f[1] = bfhi(w.x); f[2] = bflo(w.y); f[3] = bfhi(w.y); f[4] = bflo(w.z); f[5] = bfhi(w.z); f[6] = bflo(w.w); f[7] = bfhi(w.w); }
; __device__ __forceinline__ void zshift8(const Ctx& p, const bf16_t* ZRW, int row, int c, const float (&mu)[8], float (&o)[8]) {
;     float z[8], pv[8];
;     unpack8(*(const u32x4*)(ZRW + (size_t)row * SHW + c), z);
;     bool first; int bsmp = 0;
;     if (row < MPR) first = (row & (TP - 1)) == 0; else { first = ((row - MPR) & 15) == 0; bsmp = (row - MPR) >> 4; }
;     if (!first) unpack8(*(const u32x4*)(ZRW + (size_t)(row - 1) * SHW + c), pv);
;     else if (row < MPR) {
; #pragma unroll
;         for (int e = 0; e < 8; ++e) pv[e] = 0.f;
;     } else { const float* s0 = p.in(5) + (size_t)bsmp * SHW + c;
; #pragma unroll
;         for (int e = 0; e < 8; ++e) pv[e] = s0[e]; }
; #pragma unroll
;     for (int e = 0; e < 8; ++e) o[e] = z[e] + (pv[e] - z[e]) * mu[e];
; __device__ __forceinline__ void phase_lora(const Ctx& p, LAS unsigned char* lds) {
;     ...
;             const int tt = lane >> 2, cq = lane & 3, row = r0 + tt;
; #pragma unroll
;             for (int j = 0; j < 8; ++j) {
;                 const int c = cq * 64 + j * 8;
;                 float m8[8], z[8];
; #pragma unroll
;                 for (int e = 0; e < 8; ++e) m8[e] = mu[c + e];
;                 zshift8(p, ZRW, row, 1536 + c, m8, z);
; #pragma unroll
;                 for (int e = 0; e < 8; ++e) z[e] = cq == 0 ? tanhf(z[e]) : (cq == 1 ? z[e] : sigmoidf_(z[e]));
;                 u32x4 w; w.x = pk2(z[0], z[1]); w.y = pk2(z[2], z[3]); w.z = pk2(z[4], z[5]); w.w = pk2(z[6], z[7]);
;                 *(LAS u32x4*)(X + tt * 264 + c) = w;
;             }
.Llora_nf4:
	v_sub_f32_e32 v152, v152, v144
	v_sub_f32_e32 v153, v153, v145
	v_sub_f32_e32 v154, v154, v146
	v_sub_f32_e32 v155, v155, v147
	v_sub_f32_e32 v156, v156, v148
	v_sub_f32_e32 v157, v157, v149
	v_sub_f32_e32 v158, v158, v150
	v_sub_f32_e32 v159, v159, v151
	v_fmac_f32_e32 v144, v152, v112
	v_fmac_f32_e32 v145, v153, v113
	v_fmac_f32_e32 v146, v154, v114
	v_fmac_f32_e32 v147, v155, v115
	v_fmac_f32_e32 v148, v156, v116
	v_fmac_f32_e32 v149, v157, v117
	v_fmac_f32_e32 v150, v158, v118
	v_fmac_f32_e32 v151, v159, v119
	v_mul_f32_e32 v152, v7, v144
	v_mul_f32_e32 v153, v7, v145
	v_mul_f32_e32 v154, v7, v146
	v_mul_f32_e32 v155, v7, v147
	v_mul_f32_e32 v156, v7, v148
	v_mul_f32_e32 v157, v7, v149
	v_mul_f32_e32 v158, v7, v150
	v_mul_f32_e32 v159, v7, v151
	v_exp_f32_e32 v152, v152
	v_exp_f32_e32 v153, v153
	v_exp_f32_e32 v154, v154
	v_exp_f32_e32 v155, v155
	v_exp_f32_e32 v156, v156
	v_exp_f32_e32 v157, v157
	v_exp_f32_e32 v158, v158
	v_exp_f32_e32 v159, v159
	v_add_f32_e32 v152, 1.0, v152
	v_add_f32_e32 v153, 1.0, v153
	v_add_f32_e32 v154, 1.0, v154
	v_add_f32_e32 v155, 1.0, v155
	v_add_f32_e32 v156, 1.0, v156
	v_add_f32_e32 v157, 1.0, v157
	v_add_f32_e32 v158, 1.0, v158
	v_add_f32_e32 v159, 1.0, v159
	v_rcp_f32_e32 v152, v152
	v_rcp_f32_e32 v153, v153
	v_rcp_f32_e32 v154, v154
	v_rcp_f32_e32 v155, v155
	v_rcp_f32_e32 v156, v156
	v_rcp_f32_e32 v157, v157
	v_rcp_f32_e32 v158, v158
	v_rcp_f32_e32 v159, v159
	v_fma_f32 v152, v152, v8, v9
	v_fma_f32 v153, v153, v8, v9
	v_fma_f32 v154, v154, v8, v9
	v_fma_f32 v155, v155, v8, v9
	v_fma_f32 v156, v156, v8, v9
	v_fma_f32 v157, v157, v8, v9
	v_fma_f32 v158, v158, v8, v9
	v_fma_f32 v159, v159, v8, v9
	v_cndmask_b32_e64 v152, v152, v144, s[48:49]
	v_cndmask_b32_e64 v153, v153, v145, s[48:49]
	v_cndmask_b32_e64 v154, v154, v146, s[48:49]
	v_cndmask_b32_e64 v155, v155, v147, s[48:49]
	v_cndmask_b32_e64 v156, v156, v148, s[48:49]
	v_cndmask_b32_e64 v157, v157, v149, s[48:49]
	v_cndmask_b32_e64 v158, v158, v150, s[48:49]
	v_cndmask_b32_e64 v159, v159, v151, s[48:49]
	v_cvt_pk_bf16_f32 v160, v152, v153
	v_cvt_pk_bf16_f32 v161, v154, v155
	v_cvt_pk_bf16_f32 v162, v156, v157
	v_cvt_pk_bf16_f32 v163, v158, v159
	ds_write_b128 v6, v[160:163] offset:64
	v_lshlrev_b32_e32 v144, 16, v36
	v_and_b32_e32 v145, 0xffff0000, v36
	v_lshlrev_b32_e32 v152, 16, v68
	v_and_b32_e32 v153, 0xffff0000, v68
	v_lshlrev_b32_e32 v146, 16, v37
	v_and_b32_e32 v147, 0xffff0000, v37
	v_lshlrev_b32_e32 v154, 16, v69
	v_and_b32_e32 v155, 0xffff0000, v69
	v_lshlrev_b32_e32 v148, 16, v38
	v_and_b32_e32 v149, 0xffff0000, v38
	v_lshlrev_b32_e32 v156, 16, v70
	v_and_b32_e32 v157, 0xffff0000, v70
	v_lshlrev_b32_e32 v150, 16, v39
	v_and_b32_e32 v151, 0xffff0000, v39
	v_lshlrev_b32_e32 v158, 16, v71
	v_and_b32_e32 v159, 0xffff0000, v71
	s_cmp_eq_u32 s52, 0
	s_cbranch_scc1 .Llora_nf5
	s_mov_b64 s[50:51], exec
	s_mov_b64 exec, 15
	s_cmp_eq_u32 s53, 0
	s_cbranch_scc1 .Llora_pz5
	global_load_dwordx4 v[152:155], v15, s[18:19] offset:160
	global_load_dwordx4 v[156:159], v15, s[18:19] offset:176
	s_waitcnt vmcnt(0)
	s_branch .Llora_pe5

; #define LAS __attribute__((address_space(3)))
; __device__ __forceinline__ unsigned pk2(float lo, float hi) { f32x2 v = {lo, hi}; bf16x2_t b = __builtin_convertvector(v, bf16x2_t); return __builtin_bit_cast(unsigned, b); }
; __device__ __forceinline__ float sigmoidf_(float x) { return frcp(1.f + fexp2(-1.4426950408889634f * x)); }
;     __device__ __forceinline__ const float* in(int i) const { return (const float*)ptr(i); }
; __device__ __forceinline__ void unpack8(const u32x4 w, float (&f)[8]) { f[0] = bflo(w.x); f[1] = bfhi(w.x); f[2] = bflo(w.y); f[3] = bfhi(w.y); f[4] = bflo(w.z); f[5] = bfhi(w.z); f[6] = bflo(w.w); f[7] = bfhi(w.w); }
; __device__ __forceinline__ void zshift8(const Ctx& p, const bf16_t* ZRW, int row, int c, const float (&mu)[8], float (&o)[8]) {
;     float z[8], pv[8];
;     unpack8(*(const u32x4*)(ZRW + (size_t)row * SHW + c), z);
;     bool first; int bsmp = 0;
;     if (row < MPR) first = (row & (TP - 1)) == 0; else { first = ((row - MPR) & 15) == 0; bsmp = (row - MPR) >> 4; }
;     if (!first) unpack8(*(const u32x4*)(ZRW + (size_t)(row - 1) * SHW + c), pv);
;     else if (row < MPR) {
; #pragma unroll
;         for (int e = 0; e < 8; ++e) pv[e] = 0.f;
;     } else { const float* s0 = p.in(5) + (size_t)bsmp * SHW + c;
; #pragma unroll
;         for (int e = 0; e < 8; ++e) pv[e] = s0[e]; }
; #pragma unroll
;     for (int e = 0; e < 8; ++e) o[e] = z[e] + (pv[e] - z[e]) * mu[e];
; __device__ __forceinline__ void phase_lora(const Ctx& p, LAS unsigned char* lds) {
;     ...
;             const int tt = lane >> 2, cq = lane & 3, row = r0 + tt;
; #pragma unroll
;             for (int j = 0; j < 8; ++j) {
;                 const int c = cq * 64 + j * 8;
;                 float m8[8], z[8];
; #pragma unroll
;                 for (int e = 0; e < 8; ++e) m8[e] = mu[c + e];
;                 zshift8(p, ZRW, row, 1536 + c, m8, z);
; #pragma unroll
;                 for (int e = 0; e < 8; ++e) z[e] = cq == 0 ? tanhf(z[e]) : (cq == 1 ? z[e] : sigmoidf_(z[e]));
;                 u32x4 w; w.x = pk2(z[0], z[1]); w.y = pk2(z[2], z[3]); w.z = pk2(z[4], z[5]); w.w = pk2(z[6], z[7]);
;                 *(LAS u32x4*)(X + tt * 264 + c) = w;
;             }
.Llora_nf5:
	v_sub_f32_e32 v152, v152, v144
	v_sub_f32_e32 v153, v153, v145
	v_sub_f32_e32 v154, v154, v146
	v_sub_f32_e32 v155, v155, v147
	v_sub_f32_e32 v156, v156, v148
	v_sub_f32_e32 v157, v157, v149
	v_sub_f32_e32 v158, v158, v150
	v_sub_f32_e32 v159, v159, v151
	v_fmac_f32_e32 v144, v152, v120
	v_fmac_f32_e32 v145, v153, v121
	v_fmac_f32_e32 v146, v154, v122
	v_fmac_f32_e32 v147, v155, v123
	v_fmac_f32_e32 v148, v156, v124
	v_fmac_f32_e32 v149, v157, v125
	v_fmac_f32_e32 v150, v158, v126
	v_fmac_f32_e32 v151, v159, v127
	v_mul_f32_e32 v152, v7, v144
	v_mul_f32_e32 v153, v7, v145
	v_mul_f32_e32 v154, v7, v146
	v_mul_f32_e32 v155, v7, v147
	v_mul_f32_e32 v156, v7, v148
	v_mul_f32_e32 v157, v7, v149
	v_mul_f32_e32 v158, v7, v150
	v_mul_f32_e32 v159, v7, v151
	v_exp_f32_e32 v152, v152
	v_exp_f32_e32 v153, v153
	v_exp_f32_e32 v154, v154
	v_exp_f32_e32 v155, v155
	v_exp_f32_e32 v156, v156
	v_exp_f32_e32 v157, v157
	v_exp_f32_e32 v158, v158
	v_exp_f32_e32 v159, v159
	v_add_f32_e32 v152, 1.0, v152
	v_add_f32_e32 v153, 1.0, v153
	v_add_f32_e32 v154, 1.0, v154
	v_add_f32_e32 v155, 1.0, v155
	v_add_f32_e32 v156, 1.0, v156
	v_add_f32_e32 v157, 1.0, v157
	v_add_f32_e32 v158, 1.0, v158
	v_add_f32_e32 v159, 1.0, v159
	v_rcp_f32_e32 v152, v152
	v_rcp_f32_e32 v153, v153
	v_rcp_f32_e32 v154, v154
	v_rcp_f32_e32 v155, v155
	v_rcp_f32_e32 v156, v156
	v_rcp_f32_e32 v157, v157
	v_rcp_f32_e32 v158, v158
	v_rcp_f32_e32 v159, v159
	v_fma_f32 v152, v152, v8, v9
	v_fma_f32 v153, v153, v8, v9
	v_fma_f32 v154, v154, v8, v9
	v_fma_f32 v155, v155, v8, v9
	v_fma_f32 v156, v156, v8, v9
	v_fma_f32 v157, v157, v8, v9
	v_fma_f32 v158, v158, v8, v9
	v_fma_f32 v159, v159, v8, v9
	v_cndmask_b32_e64 v152, v152, v144, s[48:49]
	v_cndmask_b32_e64 v153, v153, v145, s[48:49]
	v_cndmask_b32_e64 v154, v154, v146, s[48:49]
	v_cndmask_b32_e64 v155, v155, v147, s[48:49]
	v_cndmask_b32_e64 v156, v156, v148, s[48:49]
	v_cndmask_b32_e64 v157, v157, v149, s[48:49]
	v_cndmask_b32_e64 v158, v158, v150, s[48:49]
	v_cndmask_b32_e64 v159, v159, v151, s[48:49]
	v_cvt_pk_bf16_f32 v160, v152, v153
	v_cvt_pk_bf16_f32 v161, v154, v155
	v_cvt_pk_bf16_f32 v162, v156, v157
	v_cvt_pk_bf16_f32 v163, v158, v159
	ds_write_b128 v6, v[160:163] offset:80
	v_lshlrev_b32_e32 v144, 16, v40
	v_and_b32_e32 v145, 0xffff0000, v40
	v_lshlrev_b32_e32 v152, 16, v72
	v_and_b32_e32 v153, 0xffff0000, v72
	v_lshlrev_b32_e32 v146, 16, v41
	v_and_b32_e32 v147, 0xffff0000, v41
	v_lshlrev_b32_e32 v154, 16, v73
	v_and_b32_e32 v155, 0xffff0000, v73
	v_lshlrev_b32_e32 v148, 16, v42
	v_and_b32_e32 v149, 0xffff0000, v42
	v_lshlrev_b32_e32 v156, 16, v74
	v_and_b32_e32 v157, 0xffff0000, v74
	v_lshlrev_b32_e32 v150, 16, v43
	v_and_b32_e32 v151, 0xffff0000, v43
	v_lshlrev_b32_e32 v158, 16, v75
	v_and_b32_e32 v159, 0xffff0000, v75
	s_cmp_eq_u32 s52, 0
	s_cbranch_scc1 .Llora_nf6
	s_mov_b64 s[50:51], exec
	s_mov_b64 exec, 15
	s_cmp_eq_u32 s53, 0
	s_cbranch_scc1 .Llora_pz6
	global_load_dwordx4 v[152:155], v15, s[18:19] offset:192
	global_load_dwordx4 v[156:159], v15, s[18:19] offset:208
	s_waitcnt vmcnt(0)
	s_branch .Llora_pe6

; #define LAS __attribute__((address_space(3)))
; __device__ __forceinline__ unsigned pk2(float lo, float hi) { f32x2 v = {lo, hi}; bf16x2_t b = __builtin_convertvector(v, bf16x2_t); return __builtin_bit_cast(unsigned, b); }
; __device__ __forceinline__ float sigmoidf_(float x) { return frcp(1.f + fexp2(-1.4426950408889634f * x)); }
;     __device__ __forceinline__ const float* in(int i) const { return (const float*)ptr(i); }
; __device__ __forceinline__ void unpack8(const u32x4 w, float (&f)[8]) { f[0] = bflo(w.x); f[1] = bfhi(w.x); f[2] = bflo(w.y); f[3] = bfhi(w.y); f[4] = bflo(w.z); f[5] = bfhi(w.z); f[6] = bflo(w.w); f[7] = bfhi(w.w); }
; __device__ __forceinline__ void zshift8(const Ctx& p, const bf16_t* ZRW, int row, int c, const float (&mu)[8], float (&o)[8]) {
;     float z[8], pv[8];
;     unpack8(*(const u32x4*)(ZRW + (size_t)row * SHW + c), z);
;     bool first; int bsmp = 0;
;     if (row < MPR) first = (row & (TP - 1)) == 0; else { first = ((row - MPR) & 15) == 0; bsmp = (row - MPR) >> 4; }
;     if (!first) unpack8(*(const u32x4*)(ZRW + (size_t)(row - 1) * SHW + c), pv);
;     else if (row < MPR) {
; #pragma unroll
;         for (int e = 0; e < 8; ++e) pv[e] = 0.f;
;     } else { const float* s0 = p.in(5) + (size_t)bsmp * SHW + c;
; #pragma unroll
;         for (int e = 0; e < 8; ++e) pv[e] = s0[e]; }
; #pragma unroll
;     for (int e = 0; e < 8; ++e) o[e] = z[e] + (pv[e] - z[e]) * mu[e];
; __device__ __forceinline__ void phase_lora(const Ctx& p, LAS unsigned char* lds) {
;     ...
;             const int tt = lane >> 2, cq = lane & 3, row = r0 + tt;
; #pragma unroll
;             for (int j = 0; j < 8; ++j) {
;                 const int c = cq * 64 + j * 8;
;                 float m8[8], z[8];
; #pragma unroll
;                 for (int e = 0; e < 8; ++e) m8[e] = mu[c + e];
;                 zshift8(p, ZRW, row, 1536 + c, m8, z);
; #pragma unroll
;                 for (int e = 0; e < 8; ++e) z[e] = cq == 0 ? tanhf(z[e]) : (cq == 1 ? z[e] : sigmoidf_(z[e]));
;                 u32x4 w; w.x = pk2(z[0], z[1]); w.y = pk2(z[2], z[3]); w.z = pk2(z[4], z[5]); w.w = pk2(z[6], z[7]);
;                 *(LAS u32x4*)(X + tt * 264 + c) = w;
;             }
.Llora_nf6:
	v_sub_f32_e32 v152, v152, v144
	v_sub_f32_e32 v153, v153, v145
	v_sub_f32_e32 v154, v154, v146
	v_sub_f32_e32 v155, v155, v147
	v_sub_f32_e32 v156, v156, v148
	v_sub_f32_e32 v157, v157, v149
	v_sub_f32_e32 v158, v158, v150
	v_sub_f32_e32 v159, v159, v151
	v_fmac_f32_e32 v144, v152, v128
	v_fmac_f32_e32 v145, v153, v129
	v_fmac_f32_e32 v146, v154, v130
	v_fmac_f32_e32 v147, v155, v131
	v_fmac_f32_e32 v148, v156, v132
	v_fmac_f32_e32 v149, v157, v133
	v_fmac_f32_e32 v150, v158, v134
	v_fmac_f32_e32 v151, v159, v135
	v_mul_f32_e32 v152, v7, v144
	v_mul_f32_e32 v153, v7, v145
	v_mul_f32_e32 v154, v7, v146
	v_mul_f32_e32 v155, v7, v147
	v_mul_f32_e32 v156, v7, v148
	v_mul_f32_e32 v157, v7, v149
	v_mul_f32_e32 v158, v7, v150
	v_mul_f32_e32 v159, v7, v151
	v_exp_f32_e32 v152, v152
	v_exp_f32_e32 v153, v153
	v_exp_f32_e32 v154, v154
	v_exp_f32_e32 v155, v155
	v_exp_f32_e32 v156, v156
	v_exp_f32_e32 v157, v157
	v_exp_f32_e32 v158, v158
	v_exp_f32_e32 v159, v159
	v_add_f32_e32 v152, 1.0, v152
	v_add_f32_e32 v153, 1.0, v153
	v_add_f32_e32 v154, 1.0, v154
	v_add_f32_e32 v155, 1.0, v155
	v_add_f32_e32 v156, 1.0, v156
	v_add_f32_e32 v157, 1.0, v157
	v_add_f32_e32 v158, 1.0, v158
	v_add_f32_e32 v159, 1.0, v159
	v_rcp_f32_e32 v152, v152
	v_rcp_f32_e32 v153, v153
	v_rcp_f32_e32 v154, v154
	v_rcp_f32_e32 v155, v155
	v_rcp_f32_e32 v156, v156
	v_rcp_f32_e32 v157, v157
	v_rcp_f32_e32 v158, v158
	v_rcp_f32_e32 v159, v159
	v_fma_f32 v152, v152, v8, v9
	v_fma_f32 v153, v153, v8, v9
	v_fma_f32 v154, v154, v8, v9
	v_fma_f32 v155, v155, v8, v9
	v_fma_f32 v156, v156, v8, v9
	v_fma_f32 v157, v157, v8, v9
	v_fma_f32 v158, v158, v8, v9
	v_fma_f32 v159, v159, v8, v9
	v_cndmask_b32_e64 v152, v152, v144, s[48:49]
	v_cndmask_b32_e64 v153, v153, v145, s[48:49]
	v_cndmask_b32_e64 v154, v154, v146, s[48:49]
	v_cndmask_b32_e64 v155, v155, v147, s[48:49]
	v_cndmask_b32_e64 v156, v156, v148, s[48:49]
	v_cndmask_b32_e64 v157, v157, v149, s[48:49]
	v_cndmask_b32_e64 v158, v158, v150, s[48:49]
	v_cndmask_b32_e64 v159, v159, v151, s[48:49]
	v_cvt_pk_bf16_f32 v160, v152, v153
	v_cvt_pk_bf16_f32 v161, v154, v155
	v_cvt_pk_bf16_f32 v162, v156, v157
	v_cvt_pk_bf16_f32 v163, v158, v159
	ds_write_b128 v6, v[160:163] offset:96
	v_lshlrev_b32_e32 v144, 16, v44
	v_and_b32_e32 v145, 0xffff0000, v44
	v_lshlrev_b32_e32 v152, 16, v76
	v_and_b32_e32 v153, 0xffff0000, v76
	v_lshlrev_b32_e32 v146, 16, v45
	v_and_b32_e32 v147, 0xffff0000, v45
	v_lshlrev_b32_e32 v154, 16, v77
	v_and_b32_e32 v155, 0xffff0000, v77
	v_lshlrev_b32_e32 v148, 16, v46
	v_and_b32_e32 v149, 0xffff0000, v46
	v_lshlrev_b32_e32 v156, 16, v78
	v_and_b32_e32 v157, 0xffff0000, v78
	v_lshlrev_b32_e32 v150, 16, v47
	v_and_b32_e32 v151, 0xffff0000, v47
	v_lshlrev_b32_e32 v158, 16, v79
	v_and_b32_e32 v159, 0xffff0000, v79
	s_cmp_eq_u32 s52, 0
	s_cbranch_scc1 .Llora_nf7
	s_mov_b64 s[50:51], exec
	s_mov_b64 exec, 15
	s_cmp_eq_u32 s53, 0
	s_cbranch_scc1 .Llora_pz7
	global_load_dwordx4 v[152:155], v15, s[18:19] offset:224
	global_load_dwordx4 v[156:159], v15, s[18:19] offset:240
	s_waitcnt vmcnt(0)
	s_branch .Llora_pe7

; #define LAS __attribute__((address_space(3)))
; __device__ __forceinline__ unsigned pk2(float lo, float hi) { f32x2 v = {lo, hi}; bf16x2_t b = __builtin_convertvector(v, bf16x2_t); return __builtin_bit_cast(unsigned, b); }
; __device__ __forceinline__ float sigmoidf_(float x) { return frcp(1.f + fexp2(-1.4426950408889634f * x)); }
;     __device__ __forceinline__ const float* in(int i) const { return (const float*)ptr(i); }
; __device__ __forceinline__ void phase_lora(const Ctx& p, LAS unsigned char* lds) {
;     ...
;             const int tt = lane >> 2, cq = lane & 3, row = r0 + tt;
; #pragma unroll
;             for (int j = 0; j < 8; ++j) {
;                 const int c = cq * 64 + j * 8;
;                 float m8[8], z[8];
; #pragma unroll
;                 for (int e = 0; e < 8; ++e) m8[e] = mu[c + e];
;                 zshift8(p, ZRW, row, 1536 + c, m8, z);
; #pragma unroll
;                 for (int e = 0; e < 8; ++e) z[e] = cq == 0 ? tanhf(z[e]) : (cq == 1 ? z[e] : sigmoidf_(z[e]));
;                 u32x4 w; w.x = pk2(z[0], z[1]); w.y = pk2(z[2], z[3]); w.z = pk2(z[4], z[5]); w.w = pk2(z[6], z[7]);
;                 *(LAS u32x4*)(X + tt * 264 + c) = w;
;             }
;     ...
;         asm volatile("s_waitcnt lgkmcnt(0)" ::: "memory");
;         bf16x8 bx[8];
; #pragma unroll
;         for (int ks = 0; ks < 8; ++ks) bx[ks] = *(const LAS bf16x8*)(X + q * 264 + ks * 32 + 8 * g);
;         const int row = r0 + q;
;         struct WF { bf16x8 w[2], a[2], gq[4]; f32x4 w0, a0; };
;         auto ldw = [&](WF& f, int nt) {
;             const int n = nt * 16 + q, c = nt * 16 + 4 * g;
; #pragma unroll
;             for (int ks = 0; ks < 2; ++ks) { f.w[ks] = *(const bf16x8*)(w2T + n * 64 + ks * 32 + 8 * g); f.a[ks] = *(const bf16x8*)(a2T + n * 64 + ks * 32 + 8 * g); }
; #pragma unroll
;             for (int ks = 0; ks < 4; ++ks) f.gq[ks] = *(const bf16x8*)(g2T + n * 128 + ks * 32 + 8 * g);
;             f.w0 = *(const f32x4*)(p.in(18) + c); f.a0 = *(const f32x4*)(p.in(20) + c);
;         };
.Llora_nf7:
	v_sub_f32_e32 v152, v152, v144
	v_sub_f32_e32 v153, v153, v145
	v_sub_f32_e32 v154, v154, v146
	v_sub_f32_e32 v155, v155, v147
	v_sub_f32_e32 v156, v156, v148
	v_sub_f32_e32 v157, v157, v149
	v_sub_f32_e32 v158, v158, v150
	v_sub_f32_e32 v159, v159, v151
	v_fmac_f32_e32 v144, v152, v136
	v_fmac_f32_e32 v145, v153, v137
	v_fmac_f32_e32 v146, v154, v138
	v_fmac_f32_e32 v147, v155, v139
	v_fmac_f32_e32 v148, v156, v140
	v_fmac_f32_e32 v149, v157, v141
	v_fmac_f32_e32 v150, v158, v142
	v_fmac_f32_e32 v151, v159, v143
	v_mul_f32_e32 v152, v7, v144
	v_mul_f32_e32 v153, v7, v145
	v_mul_f32_e32 v154, v7, v146
	v_mul_f32_e32 v155, v7, v147
	v_mul_f32_e32 v156, v7, v148
	v_mul_f32_e32 v157, v7, v149
	v_mul_f32_e32 v158, v7, v150
	v_mul_f32_e32 v159, v7, v151
	v_exp_f32_e32 v152, v152
	v_exp_f32_e32 v153, v153
	v_exp_f32_e32 v154, v154
	v_exp_f32_e32 v155, v155
	v_exp_f32_e32 v156, v156
	v_exp_f32_e32 v157, v157
	v_exp_f32_e32 v158, v158
	v_exp_f32_e32 v159, v159
	v_add_f32_e32 v152, 1.0, v152
	v_add_f32_e32 v153, 1.0, v153
	v_add_f32_e32 v154, 1.0, v154
	v_add_f32_e32 v155, 1.0, v155
	v_add_f32_e32 v156, 1.0, v156
	v_add_f32_e32 v157, 1.0, v157
	v_add_f32_e32 v158, 1.0, v158
	v_add_f32_e32 v159, 1.0, v159
	v_rcp_f32_e32 v152, v152
	v_rcp_f32_e32 v153, v153
	v_rcp_f32_e32 v154, v154
	v_rcp_f32_e32 v155, v155
	v_rcp_f32_e32 v156, v156
	v_rcp_f32_e32 v157, v157
	v_rcp_f32_e32 v158, v158
	v_rcp_f32_e32 v159, v159
	v_fma_f32 v152, v152, v8, v9
	v_fma_f32 v153, v153, v8, v9
	v_fma_f32 v154, v154, v8, v9
	v_fma_f32 v155, v155, v8, v9
	v_fma_f32 v156, v156, v8, v9
	v_fma_f32 v157, v157, v8, v9
	v_fma_f32 v158, v158, v8, v9
	v_fma_f32 v159, v159, v8, v9
	v_cndmask_b32_e64 v152, v152, v144, s[48:49]
	v_cndmask_b32_e64 v153, v153, v145, s[48:49]
	v_cndmask_b32_e64 v154, v154, v146, s[48:49]
	v_cndmask_b32_e64 v155, v155, v147, s[48:49]
	v_cndmask_b32_e64 v156, v156, v148, s[48:49]
	v_cndmask_b32_e64 v157, v157, v149, s[48:49]
	v_cndmask_b32_e64 v158, v158, v150, s[48:49]
	v_cndmask_b32_e64 v159, v159, v151, s[48:49]
	v_cvt_pk_bf16_f32 v160, v152, v153
	v_cvt_pk_bf16_f32 v161, v154, v155
	v_cvt_pk_bf16_f32 v162, v156, v157
	v_cvt_pk_bf16_f32 v163, v158, v159
	ds_write_b128 v6, v[160:163] offset:112
	s_waitcnt lgkmcnt(0)
	ds_read_b128 v[184:187], v14 offset:0
	ds_read_b128 v[188:191], v14 offset:64
	ds_read_b128 v[192:195], v14 offset:128
	ds_read_b128 v[196:199], v14 offset:192
	ds_read_b128 v[200:203], v14 offset:256
	ds_read_b128 v[204:207], v14 offset:320
	ds_read_b128 v[208:211], v14 offset:384
	ds_read_b128 v[212:215], v14 offset:448
	s_lshl_b32 s2, s26, 4
	v_add_u32_e32 v137, s2, v10
	v_lshlrev_b32_e32 v132, 7, v10
	v_lshl_add_u32 v132, v11, 4, v132
	v_lshlrev_b32_e32 v133, 8, v10
	v_lshl_add_u32 v133, v11, 4, v133
	v_lshlrev_b32_e32 v134, 4, v11
	v_lshlrev_b32_e32 v135, 11, v137
	v_lshl_add_u32 v135, v11, 4, v135
	v_lshlrev_b32_e32 v136, 10, v137
	v_lshl_add_u32 v136, v11, 3, v136
	s_lshl_b32 s2, s56, 15
	v_add_u32_e32 v132, s2, v132
	s_lshl_b32 s2, s56, 16
	v_add_u32_e32 v133, s2, v133
	s_lshl_b32 s2, s56, 10
	v_add_u32_e32 v134, s2, v134
	v_add_u32_e32 v135, s2, v135
	s_lshl_b32 s2, s56, 9
	v_add_u32_e32 v136, s2, v136
	global_load_dwordx4 v[16:19], v132, s[24:25]
	global_load_dwordx4 v[20:23], v132, s[24:25] offset:64
	global_load_dwordx4 v[24:27], v132, s[40:41]
	global_load_dwordx4 v[28:31], v132, s[40:41] offset:64
	global_load_dwordx4 v[32:35], v133, s[42:43]
	global_load_dwordx4 v[36:39], v133, s[42:43] offset:64
	global_load_dwordx4 v[40:43], v133, s[42:43] offset:128
	global_load_dwordx4 v[44:47], v133, s[42:43] offset:192
	global_load_dwordx4 v[48:51], v134, s[20:21]
	global_load_dwordx4 v[52:55], v134, s[22:23]
	v_add_u32_e32 v132, 0x800, v132
	v_add_u32_e32 v133, 0x1000, v133
	v_add_u32_e32 v134, 64, v134
	s_waitcnt lgkmcnt(0)
	global_load_dwordx4 v[56:59], v132, s[24:25]
	global_load_dwordx4 v[60:63], v132, s[24:25] offset:64
	global_load_dwordx4 v[64:67], v132, s[40:41]
	global_load_dwordx4 v[68:71], v132, s[40:41] offset:64
	global_load_dwordx4 v[72:75], v133, s[42:43]
	global_load_dwordx4 v[76:79], v133, s[42:43] offset:64
	global_load_dwordx4 v[80:83], v133, s[42:43] offset:128
	global_load_dwordx4 v[84:87], v133, s[42:43] offset:192
	global_load_dwordx4 v[88:91], v134, s[20:21]
	global_load_dwordx4 v[92:95], v134, s[22:23]
	s_waitcnt vmcnt(10)
; __device__ __forceinline__ unsigned pk2(float lo, float hi) { f32x2 v = {lo, hi}; bf16x2_t b = __builtin_convertvector(v, bf16x2_t); return __builtin_bit_cast(unsigned, b); }
; __device__ __forceinline__ float sigmoidf_(float x) { return frcp(1.f + fexp2(-1.4426950408889634f * x)); }
; __device__ __forceinline__ void phase_lora(const Ctx& p, LAS unsigned char* lds) {
;     ...
;         auto tile = [&](const WF& f, int nt) {
;             f32x4 aw = (f32x4){0.f, 0.f, 0.f, 0.f}, aa = aw, ag = aw;
; #pragma unroll
;             for (int ks = 0; ks < 2; ++ks) { aw = __builtin_amdgcn_mfma_f32_16x16x32_bf16(f.w[ks], bx[ks], aw, 0, 0, 0); aa = __builtin_amdgcn_mfma_f32_16x16x32_bf16(f.a[ks], bx[2 + ks], aa, 0, 0, 0); }
; #pragma unroll
;             for (int ks = 0; ks < 4; ++ks) ag = __builtin_amdgcn_mfma_f32_16x16x32_bf16(f.gq[ks], bx[4 + ks], ag, 0, 0, 0);
;             const int c = nt * 16 + 4 * g;
;             f32x4 dec; float av[4];
; #pragma unroll
;             for (int e = 0; e < 4; ++e) {
;                 const float x = f.w0[e] + aw[e];
;                 const float sp = fmaxf(-x, 0.f) + log1pf(expf(-fabsf(x)));
;                 dec[e] = expf(-expf(-sp - 0.5f));
;                 av[e] = sigmoidf_(f.a0[e] + aa[e]);
;             }
;             *(f32x4*)(DEC + (size_t)row * 512 + c) = dec;
;             *(u32x2*)(AB + (size_t)row * 512 + c) = (u32x2){pk2(av[0], av[1]), pk2(av[2], av[3])};
;             *(u32x2*)(GG + (size_t)row * 512 + c) = (u32x2){pk2(ag[0], ag[1]), pk2(ag[2], ag[3])};
;         };
	v_mfma_f32_16x16x32_bf16 v[96:99], v[16:19], v[184:187], 0
	v_mfma_f32_16x16x32_bf16 v[100:103], v[24:27], v[192:195], 0
	v_mfma_f32_16x16x32_bf16 v[104:107], v[32:35], v[200:203], 0
	v_mfma_f32_16x16x32_bf16 v[96:99], v[20:23], v[188:191], v[96:99]
	v_mfma_f32_16x16x32_bf16 v[100:103], v[28:31], v[196:199], v[100:103]
	v_mfma_f32_16x16x32_bf16 v[104:107], v[36:39], v[204:207], v[104:107]
	v_mfma_f32_16x16x32_bf16 v[104:107], v[40:43], v[208:211], v[104:107]
	v_mfma_f32_16x16x32_bf16 v[104:107], v[44:47], v[212:215], v[104:107]
	v_add_u32_e32 v132, 0x800, v132
	v_add_u32_e32 v133, 0x1000, v133
	v_add_u32_e32 v134, 64, v134
	s_nop 4
	v_add_f32_e32 v108, v48, v96
	v_add_f32_e32 v109, v49, v97
	v_add_f32_e32 v110, v50, v98
	v_add_f32_e32 v111, v51, v99
	v_add_f32_e32 v112, v52, v100
	v_add_f32_e32 v113, v53, v101
	v_add_f32_e32 v114, v54, v102
	v_add_f32_e32 v115, v55, v103
	v_mul_f32_e32 v108, 0xbfb8aa3b, v108
	v_mul_f32_e32 v109, 0xbfb8aa3b, v109
	v_mul_f32_e32 v110, 0xbfb8aa3b, v110
	v_mul_f32_e32 v111, 0xbfb8aa3b, v111
	v_mul_f32_e32 v112, 0xbfb8aa3b, v112
	v_mul_f32_e32 v113, 0xbfb8aa3b, v113
	v_mul_f32_e32 v114, 0xbfb8aa3b, v114
	v_mul_f32_e32 v115, 0xbfb8aa3b, v115
	v_exp_f32_e32 v108, v108
	v_exp_f32_e32 v109, v109
	v_exp_f32_e32 v110, v110
	v_exp_f32_e32 v111, v111
	v_exp_f32_e32 v112, v112
	v_exp_f32_e32 v113, v113
	v_exp_f32_e32 v114, v114
	v_exp_f32_e32 v115, v115
	v_add_f32_e32 v108, 1.0, v108
	v_add_f32_e32 v109, 1.0, v109
	v_add_f32_e32 v110, 1.0, v110
	v_add_f32_e32 v111, 1.0, v111
	v_add_f32_e32 v112, 1.0, v112
	v_add_f32_e32 v113, 1.0, v113
	v_add_f32_e32 v114, 1.0, v114
	v_add_f32_e32 v115, 1.0, v115
	v_rcp_f32_e32 v108, v108
	v_rcp_f32_e32 v109, v109
	v_rcp_f32_e32 v110, v110
	v_rcp_f32_e32 v111, v111
	v_rcp_f32_e32 v112, v112
	v_rcp_f32_e32 v113, v113
	v_rcp_f32_e32 v114, v114
	v_rcp_f32_e32 v115, v115
	v_mul_f32_e32 v108, 0xbf60028b, v108
	v_mul_f32_e32 v109, 0xbf60028b, v109
	v_mul_f32_e32 v110, 0xbf60028b, v110
	v_mul_f32_e32 v111, 0xbf60028b, v111
	v_cvt_pk_bf16_f32 v116, v112, v113
	v_cvt_pk_bf16_f32 v117, v114, v115
	v_exp_f32_e32 v108, v108
	v_exp_f32_e32 v109, v109
	v_exp_f32_e32 v110, v110
	v_exp_f32_e32 v111, v111
	v_cvt_pk_bf16_f32 v118, v104, v105
	v_cvt_pk_bf16_f32 v119, v106, v107
	global_store_dwordx2 v136, v[116:117], s[44:45]
	global_store_dwordx2 v136, v[118:119], s[46:47]
	global_store_dwordx4 v135, v[108:111], s[54:55]
	v_add_u32_e32 v136, 32, v136
	v_add_u32_e32 v135, 64, v135
	global_load_dwordx4 v[16:19], v132, s[24:25]
	global_load_dwordx4 v[20:23], v132, s[24:25] offset:64
	global_load_dwordx4 v[24:27], v132, s[40:41]
	global_load_dwordx4 v[28:31], v132, s[40:41] offset:64
	global_load_dwordx4 v[32:35], v133, s[42:43]
	global_load_dwordx4 v[36:39], v133, s[42:43] offset:64
	global_load_dwordx4 v[40:43], v133, s[42:43] offset:128
	global_load_dwordx4 v[44:47], v133, s[42:43] offset:192
	global_load_dwordx4 v[48:51], v134, s[20:21]
	global_load_dwordx4 v[52:55], v134, s[22:23]
	s_waitcnt vmcnt(13)
	v_mfma_f32_16x16x32_bf16 v[96:99], v[56:59], v[184:187], 0
	v_mfma_f32_16x16x32_bf16 v[100:103], v[64:67], v[192:195], 0
	v_mfma_f32_16x16x32_bf16 v[104:107], v[72:75], v[200:203], 0
	v_mfma_f32_16x16x32_bf16 v[96:99], v[60:63], v[188:191], v[96:99]
	v_mfma_f32_16x16x32_bf16 v[100:103], v[68:71], v[196:199], v[100:103]
	v_mfma_f32_16x16x32_bf16 v[104:107], v[76:79], v[204:207], v[104:107]
	v_mfma_f32_16x16x32_bf16 v[104:107], v[80:83], v[208:211], v[104:107]
	v_mfma_f32_16x16x32_bf16 v[104:107], v[84:87], v[212:215], v[104:107]
	v_add_u32_e32 v132, 0x800, v132
	v_add_u32_e32 v133, 0x1000, v133
	v_add_u32_e32 v134, 64, v134
	s_nop 4
	v_add_f32_e32 v108, v88, v96
	v_add_f32_e32 v109, v89, v97
	v_add_f32_e32 v110, v90, v98
	v_add_f32_e32 v111, v91, v99
	v_add_f32_e32 v112, v92, v100
	v_add_f32_e32 v113, v93, v101
	v_add_f32_e32 v114, v94, v102
	v_add_f32_e32 v115, v95, v103
	v_mul_f32_e32 v108, 0xbfb8aa3b, v108
	v_mul_f32_e32 v109, 0xbfb8aa3b, v109
	v_mul_f32_e32 v110, 0xbfb8aa3b, v110
	v_mul_f32_e32 v111, 0xbfb8aa3b, v111
	v_mul_f32_e32 v112, 0xbfb8aa3b, v112
	v_mul_f32_e32 v113, 0xbfb8aa3b, v113
	v_mul_f32_e32 v114, 0xbfb8aa3b, v114
	v_mul_f32_e32 v115, 0xbfb8aa3b, v115
	v_exp_f32_e32 v108, v108
	v_exp_f32_e32 v109, v109
	v_exp_f32_e32 v110, v110
	v_exp_f32_e32 v111, v111
	v_exp_f32_e32 v112, v112
	v_exp_f32_e32 v113, v113
	v_exp_f32_e32 v114, v114
	v_exp_f32_e32 v115, v115
	v_add_f32_e32 v108, 1.0, v108
	v_add_f32_e32 v109, 1.0, v109
	v_add_f32_e32 v110, 1.0, v110
	v_add_f32_e32 v111, 1.0, v111
	v_add_f32_e32 v112, 1.0, v112
	v_add_f32_e32 v113, 1.0, v113
	v_add_f32_e32 v114, 1.0, v114
	v_add_f32_e32 v115, 1.0, v115
	v_rcp_f32_e32 v108, v108
	v_rcp_f32_e32 v109, v109
	v_rcp_f32_e32 v110, v110
	v_rcp_f32_e32 v111, v111
	v_rcp_f32_e32 v112, v112
	v_rcp_f32_e32 v113, v113
	v_rcp_f32_e32 v114, v114
	v_rcp_f32_e32 v115, v115
	v_mul_f32_e32 v108, 0xbf60028b, v108
	v_mul_f32_e32 v109, 0xbf60028b, v109
	v_mul_f32_e32 v110, 0xbf60028b, v110
	v_mul_f32_e32 v111, 0xbf60028b, v111
	v_cvt_pk_bf16_f32 v116, v112, v113
	v_cvt_pk_bf16_f32 v117, v114, v115
	v_exp_f32_e32 v108, v108
	v_exp_f32_e32 v109, v109
	v_exp_f32_e32 v110, v110
	v_exp_f32_e32 v111, v111
	v_cvt_pk_bf16_f32 v118, v104, v105
	v_cvt_pk_bf16_f32 v119, v106, v107
	global_store_dwordx2 v136, v[116:117], s[44:45]
	global_store_dwordx2 v136, v[118:119], s[46:47]
	global_store_dwordx4 v135, v[108:111], s[54:55]
	v_add_u32_e32 v136, 32, v136
	v_add_u32_e32 v135, 64, v135
	s_movk_i32 s2, 6
; __device__ __forceinline__ unsigned pk2(float lo, float hi) { f32x2 v = {lo, hi}; bf16x2_t b = __builtin_convertvector(v, bf16x2_t); return __builtin_bit_cast(unsigned, b); }
; __device__ __forceinline__ float sigmoidf_(float x) { return frcp(1.f + fexp2(-1.4426950408889634f * x)); }
; __device__ __forceinline__ void phase_lora(const Ctx& p, LAS unsigned char* lds) {
;     ...
;         auto tile = [&](const WF& f, int nt) {
;             f32x4 aw = (f32x4){0.f, 0.f, 0.f, 0.f}, aa = aw, ag = aw;
; #pragma unroll
;             for (int ks = 0; ks < 2; ++ks) { aw = __builtin_amdgcn_mfma_f32_16x16x32_bf16(f.w[ks], bx[ks], aw, 0, 0, 0); aa = __builtin_amdgcn_mfma_f32_16x16x32_bf16(f.a[ks], bx[2 + ks], aa, 0, 0, 0); }
; #pragma unroll
;             for (int ks = 0; ks < 4; ++ks) ag = __builtin_amdgcn_mfma_f32_16x16x32_bf16(f.gq[ks], bx[4 + ks], ag, 0, 0, 0);
;             const int c = nt * 16 + 4 * g;
;             f32x4 dec; float av[4];
; #pragma unroll
;             for (int e = 0; e < 4; ++e) {
;                 const float x = f.w0[e] + aw[e];
;                 const float sp = fmaxf(-x, 0.f) + log1pf(expf(-fabsf(x)));
;                 dec[e] = expf(-expf(-sp - 0.5f));
;                 av[e] = sigmoidf_(f.a0[e] + aa[e]);
;             }
;             *(f32x4*)(DEC + (size_t)row * 512 + c) = dec;
;             *(u32x2*)(AB + (size_t)row * 512 + c) = (u32x2){pk2(av[0], av[1]), pk2(av[2], av[3])};
;             *(u32x2*)(GG + (size_t)row * 512 + c) = (u32x2){pk2(ag[0], ag[1]), pk2(ag[2], ag[3])};
;         };
;     ...
; #pragma unroll 1
;         for (int nt = 0; nt < 32; nt += 2) {
;             ldw(fb, nt + 1);
;             tile(fa, nt);
;             ldw(fa, (nt + 2) & 31);
;             tile(fb, nt + 1);
;         }
.Llora_nt:
	global_load_dwordx4 v[56:59], v132, s[24:25]
	global_load_dwordx4 v[60:63], v132, s[24:25] offset:64
	global_load_dwordx4 v[64:67], v132, s[40:41]
	global_load_dwordx4 v[68:71], v132, s[40:41] offset:64
	global_load_dwordx4 v[72:75], v133, s[42:43]
	global_load_dwordx4 v[76:79], v133, s[42:43] offset:64
	global_load_dwordx4 v[80:83], v133, s[42:43] offset:128
	global_load_dwordx4 v[84:87], v133, s[42:43] offset:192
	global_load_dwordx4 v[88:91], v134, s[20:21]
	global_load_dwordx4 v[92:95], v134, s[22:23]
	s_waitcnt vmcnt(13)
	v_mfma_f32_16x16x32_bf16 v[96:99], v[16:19], v[184:187], 0
	v_mfma_f32_16x16x32_bf16 v[100:103], v[24:27], v[192:195], 0
	v_mfma_f32_16x16x32_bf16 v[104:107], v[32:35], v[200:203], 0
	v_mfma_f32_16x16x32_bf16 v[96:99], v[20:23], v[188:191], v[96:99]
	v_mfma_f32_16x16x32_bf16 v[100:103], v[28:31], v[196:199], v[100:103]
	v_mfma_f32_16x16x32_bf16 v[104:107], v[36:39], v[204:207], v[104:107]
	v_mfma_f32_16x16x32_bf16 v[104:107], v[40:43], v[208:211], v[104:107]
	v_mfma_f32_16x16x32_bf16 v[104:107], v[44:47], v[212:215], v[104:107]
	v_add_u32_e32 v132, 0x800, v132
	v_add_u32_e32 v133, 0x1000, v133
	v_add_u32_e32 v134, 64, v134
	s_nop 4
	v_add_f32_e32 v108, v48, v96
	v_add_f32_e32 v109, v49, v97
	v_add_f32_e32 v110, v50, v98
	v_add_f32_e32 v111, v51, v99
	v_add_f32_e32 v112, v52, v100
	v_add_f32_e32 v113, v53, v101
	v_add_f32_e32 v114, v54, v102
	v_add_f32_e32 v115, v55, v103
	v_mul_f32_e32 v108, 0xbfb8aa3b, v108
	v_mul_f32_e32 v109, 0xbfb8aa3b, v109
	v_mul_f32_e32 v110, 0xbfb8aa3b, v110
	v_mul_f32_e32 v111, 0xbfb8aa3b, v111
	v_mul_f32_e32 v112, 0xbfb8aa3b, v112
	v_mul_f32_e32 v113, 0xbfb8aa3b, v113
	v_mul_f32_e32 v114, 0xbfb8aa3b, v114
	v_mul_f32_e32 v115, 0xbfb8aa3b, v115
	v_exp_f32_e32 v108, v108
	v_exp_f32_e32 v109, v109
	v_exp_f32_e32 v110, v110
	v_exp_f32_e32 v111, v111
	v_exp_f32_e32 v112, v112
	v_exp_f32_e32 v113, v113
	v_exp_f32_e32 v114, v114
	v_exp_f32_e32 v115, v115
	v_add_f32_e32 v108, 1.0, v108
	v_add_f32_e32 v109, 1.0, v109
	v_add_f32_e32 v110, 1.0, v110
	v_add_f32_e32 v111, 1.0, v111
	v_add_f32_e32 v112, 1.0, v112
	v_add_f32_e32 v113, 1.0, v113
	v_add_f32_e32 v114, 1.0, v114
	v_add_f32_e32 v115, 1.0, v115
	v_rcp_f32_e32 v108, v108
	v_rcp_f32_e32 v109, v109
	v_rcp_f32_e32 v110, v110
	v_rcp_f32_e32 v111, v111
	v_rcp_f32_e32 v112, v112
	v_rcp_f32_e32 v113, v113
	v_rcp_f32_e32 v114, v114
	v_rcp_f32_e32 v115, v115
	v_mul_f32_e32 v108, 0xbf60028b, v108
	v_mul_f32_e32 v109, 0xbf60028b, v109
	v_mul_f32_e32 v110, 0xbf60028b, v110
	v_mul_f32_e32 v111, 0xbf60028b, v111
	v_cvt_pk_bf16_f32 v116, v112, v113
	v_cvt_pk_bf16_f32 v117, v114, v115
	v_exp_f32_e32 v108, v108
	v_exp_f32_e32 v109, v109
	v_exp_f32_e32 v110, v110
	v_exp_f32_e32 v111, v111
	v_cvt_pk_bf16_f32 v118, v104, v105
	v_cvt_pk_bf16_f32 v119, v106, v107
	global_store_dwordx2 v136, v[116:117], s[44:45]
	global_store_dwordx2 v136, v[118:119], s[46:47]
	global_store_dwordx4 v135, v[108:111], s[54:55]
	v_add_u32_e32 v136, 32, v136
	v_add_u32_e32 v135, 64, v135
	global_load_dwordx4 v[16:19], v132, s[24:25]
	global_load_dwordx4 v[20:23], v132, s[24:25] offset:64
	global_load_dwordx4 v[24:27], v132, s[40:41]
	global_load_dwordx4 v[28:31], v132, s[40:41] offset:64
	global_load_dwordx4 v[32:35], v133, s[42:43]
	global_load_dwordx4 v[36:39], v133, s[42:43] offset:64
	global_load_dwordx4 v[40:43], v133, s[42:43] offset:128
	global_load_dwordx4 v[44:47], v133, s[42:43] offset:192
	global_load_dwordx4 v[48:51], v134, s[20:21]
	global_load_dwordx4 v[52:55], v134, s[22:23]
	s_waitcnt vmcnt(13)
	v_mfma_f32_16x16x32_bf16 v[96:99], v[56:59], v[184:187], 0
	v_mfma_f32_16x16x32_bf16 v[100:103], v[64:67], v[192:195], 0
	v_mfma_f32_16x16x32_bf16 v[104:107], v[72:75], v[200:203], 0
	v_mfma_f32_16x16x32_bf16 v[96:99], v[60:63], v[188:191], v[96:99]
	v_mfma_f32_16x16x32_bf16 v[100:103], v[68:71], v[196:199], v[100:103]
	v_mfma_f32_16x16x32_bf16 v[104:107], v[76:79], v[204:207], v[104:107]
	v_mfma_f32_16x16x32_bf16 v[104:107], v[80:83], v[208:211], v[104:107]
	v_mfma_f32_16x16x32_bf16 v[104:107], v[84:87], v[212:215], v[104:107]
	v_add_u32_e32 v132, 0x800, v132
	v_add_u32_e32 v133, 0x1000, v133
	v_add_u32_e32 v134, 64, v134
	s_nop 4
	v_add_f32_e32 v108, v88, v96
	v_add_f32_e32 v109, v89, v97
	v_add_f32_e32 v110, v90, v98
	v_add_f32_e32 v111, v91, v99
	v_add_f32_e32 v112, v92, v100
	v_add_f32_e32 v113, v93, v101
	v_add_f32_e32 v114, v94, v102
	v_add_f32_e32 v115, v95, v103
	v_mul_f32_e32 v108, 0xbfb8aa3b, v108
	v_mul_f32_e32 v109, 0xbfb8aa3b, v109
	v_mul_f32_e32 v110, 0xbfb8aa3b, v110
	v_mul_f32_e32 v111, 0xbfb8aa3b, v111
	v_mul_f32_e32 v112, 0xbfb8aa3b, v112
	v_mul_f32_e32 v113, 0xbfb8aa3b, v113
	v_mul_f32_e32 v114, 0xbfb8aa3b, v114
	v_mul_f32_e32 v115, 0xbfb8aa3b, v115
	v_exp_f32_e32 v108, v108
	v_exp_f32_e32 v109, v109
	v_exp_f32_e32 v110, v110
	v_exp_f32_e32 v111, v111
	v_exp_f32_e32 v112, v112
	v_exp_f32_e32 v113, v113
	v_exp_f32_e32 v114, v114
	v_exp_f32_e32 v115, v115
	v_add_f32_e32 v108, 1.0, v108
	v_add_f32_e32 v109, 1.0, v109
	v_add_f32_e32 v110, 1.0, v110
	v_add_f32_e32 v111, 1.0, v111
	v_add_f32_e32 v112, 1.0, v112
	v_add_f32_e32 v113, 1.0, v113
	v_add_f32_e32 v114, 1.0, v114
	v_add_f32_e32 v115, 1.0, v115
	v_rcp_f32_e32 v108, v108
	v_rcp_f32_e32 v109, v109
	v_rcp_f32_e32 v110, v110
	v_rcp_f32_e32 v111, v111
	v_rcp_f32_e32 v112, v112
	v_rcp_f32_e32 v113, v113
	v_rcp_f32_e32 v114, v114
	v_rcp_f32_e32 v115, v115
	v_mul_f32_e32 v108, 0xbf60028b, v108
	v_mul_f32_e32 v109, 0xbf60028b, v109
	v_mul_f32_e32 v110, 0xbf60028b, v110
	v_mul_f32_e32 v111, 0xbf60028b, v111
	v_cvt_pk_bf16_f32 v116, v112, v113
	v_cvt_pk_bf16_f32 v117, v114, v115
	v_exp_f32_e32 v108, v108
	v_exp_f32_e32 v109, v109
	v_exp_f32_e32 v110, v110
	v_exp_f32_e32 v111, v111
	v_cvt_pk_bf16_f32 v118, v104, v105
	v_cvt_pk_bf16_f32 v119, v106, v107
	global_store_dwordx2 v136, v[116:117], s[44:45]
	global_store_dwordx2 v136, v[118:119], s[46:47]
	global_store_dwordx4 v135, v[108:111], s[54:55]
	v_add_u32_e32 v136, 32, v136
	v_add_u32_e32 v135, 64, v135
	s_sub_u32 s2, s2, 1
	s_cmp_lg_u32 s2, 0
	s_cbranch_scc1 .Llora_nt
; __device__ __forceinline__ void phase_lora(const Ctx& p, LAS unsigned char* lds) {
;     ...
;     for (int it = blockIdx.x + gridDim.x * wave; it < MR / 16; it += gridDim.x * 8) {
;     ...
; #pragma unroll 1
;         for (int nt = 0; nt < 32; nt += 2) {
;             ldw(fb, nt + 1);
;             tile(fa, nt);
;             ldw(fa, (nt + 2) & 31);
;             tile(fb, nt + 1);
;         }
	global_load_dwordx4 v[56:59], v132, s[24:25]
	global_load_dwordx4 v[60:63], v132, s[24:25] offset:64
	global_load_dwordx4 v[64:67], v132, s[40:41]
	global_load_dwordx4 v[68:71], v132, s[40:41] offset:64
	global_load_dwordx4 v[72:75], v133, s[42:43]
	global_load_dwordx4 v[76:79], v133, s[42:43] offset:64
	global_load_dwordx4 v[80:83], v133, s[42:43] offset:128
	global_load_dwordx4 v[84:87], v133, s[42:43] offset:192
	global_load_dwordx4 v[88:91], v134, s[20:21]
	global_load_dwordx4 v[92:95], v134, s[22:23]
	s_waitcnt vmcnt(13)
	v_mfma_f32_16x16x32_bf16 v[96:99], v[16:19], v[184:187], 0
	v_mfma_f32_16x16x32_bf16 v[100:103], v[24:27], v[192:195], 0
	v_mfma_f32_16x16x32_bf16 v[104:107], v[32:35], v[200:203], 0
	v_mfma_f32_16x16x32_bf16 v[96:99], v[20:23], v[188:191], v[96:99]
	v_mfma_f32_16x16x32_bf16 v[100:103], v[28:31], v[196:199], v[100:103]
	v_mfma_f32_16x16x32_bf16 v[104:107], v[36:39], v[204:207], v[104:107]
	v_mfma_f32_16x16x32_bf16 v[104:107], v[40:43], v[208:211], v[104:107]
	v_mfma_f32_16x16x32_bf16 v[104:107], v[44:47], v[212:215], v[104:107]
	v_add_u32_e32 v132, 0x800, v132
	v_add_u32_e32 v133, 0x1000, v133
	v_add_u32_e32 v134, 64, v134
	s_nop 4
	v_add_f32_e32 v108, v48, v96
	v_add_f32_e32 v109, v49, v97
	v_add_f32_e32 v110, v50, v98
	v_add_f32_e32 v111, v51, v99
	v_add_f32_e32 v112, v52, v100
	v_add_f32_e32 v113, v53, v101
	v_add_f32_e32 v114, v54, v102
	v_add_f32_e32 v115, v55, v103
	v_mul_f32_e32 v108, 0xbfb8aa3b, v108
	v_mul_f32_e32 v109, 0xbfb8aa3b, v109
	v_mul_f32_e32 v110, 0xbfb8aa3b, v110
	v_mul_f32_e32 v111, 0xbfb8aa3b, v111
	v_mul_f32_e32 v112, 0xbfb8aa3b, v112
	v_mul_f32_e32 v113, 0xbfb8aa3b, v113
	v_mul_f32_e32 v114, 0xbfb8aa3b, v114
	v_mul_f32_e32 v115, 0xbfb8aa3b, v115
	v_exp_f32_e32 v108, v108
	v_exp_f32_e32 v109, v109
	v_exp_f32_e32 v110, v110
	v_exp_f32_e32 v111, v111
	v_exp_f32_e32 v112, v112
	v_exp_f32_e32 v113, v113
	v_exp_f32_e32 v114, v114
	v_exp_f32_e32 v115, v115
	v_add_f32_e32 v108, 1.0, v108
	v_add_f32_e32 v109, 1.0, v109
	v_add_f32_e32 v110, 1.0, v110
	v_add_f32_e32 v111, 1.0, v111
	v_add_f32_e32 v112, 1.0, v112
	v_add_f32_e32 v113, 1.0, v113
	v_add_f32_e32 v114, 1.0, v114
	v_add_f32_e32 v115, 1.0, v115
	v_rcp_f32_e32 v108, v108
	v_rcp_f32_e32 v109, v109
	v_rcp_f32_e32 v110, v110
	v_rcp_f32_e32 v111, v111
	v_rcp_f32_e32 v112, v112
	v_rcp_f32_e32 v113, v113
	v_rcp_f32_e32 v114, v114
	v_rcp_f32_e32 v115, v115
	v_mul_f32_e32 v108, 0xbf60028b, v108
	v_mul_f32_e32 v109, 0xbf60028b, v109
	v_mul_f32_e32 v110, 0xbf60028b, v110
	v_mul_f32_e32 v111, 0xbf60028b, v111
	v_cvt_pk_bf16_f32 v116, v112, v113
	v_cvt_pk_bf16_f32 v117, v114, v115
	v_exp_f32_e32 v108, v108
	v_exp_f32_e32 v109, v109
	v_exp_f32_e32 v110, v110
	v_exp_f32_e32 v111, v111
	v_cvt_pk_bf16_f32 v118, v104, v105
	v_cvt_pk_bf16_f32 v119, v106, v107
	global_store_dwordx2 v136, v[116:117], s[44:45]
	global_store_dwordx2 v136, v[118:119], s[46:47]
	global_store_dwordx4 v135, v[108:111], s[54:55]
	v_add_u32_e32 v136, 32, v136
	v_add_u32_e32 v135, 64, v135
	s_waitcnt vmcnt(3)
	v_mfma_f32_16x16x32_bf16 v[96:99], v[56:59], v[184:187], 0
	v_mfma_f32_16x16x32_bf16 v[100:103], v[64:67], v[192:195], 0
	v_mfma_f32_16x16x32_bf16 v[104:107], v[72:75], v[200:203], 0
	v_mfma_f32_16x16x32_bf16 v[96:99], v[60:63], v[188:191], v[96:99]
	v_mfma_f32_16x16x32_bf16 v[100:103], v[68:71], v[196:199], v[100:103]
	v_mfma_f32_16x16x32_bf16 v[104:107], v[76:79], v[204:207], v[104:107]
	v_mfma_f32_16x16x32_bf16 v[104:107], v[80:83], v[208:211], v[104:107]
	v_mfma_f32_16x16x32_bf16 v[104:107], v[84:87], v[212:215], v[104:107]
	v_add_u32_e32 v132, 0x800, v132
	v_add_u32_e32 v133, 0x1000, v133
	v_add_u32_e32 v134, 64, v134
	s_nop 4
	v_add_f32_e32 v108, v88, v96
	v_add_f32_e32 v109, v89, v97
	v_add_f32_e32 v110, v90, v98
	v_add_f32_e32 v111, v91, v99
	v_add_f32_e32 v112, v92, v100
	v_add_f32_e32 v113, v93, v101
	v_add_f32_e32 v114, v94, v102
	v_add_f32_e32 v115, v95, v103
	v_mul_f32_e32 v108, 0xbfb8aa3b, v108
	v_mul_f32_e32 v109, 0xbfb8aa3b, v109
	v_mul_f32_e32 v110, 0xbfb8aa3b, v110
	v_mul_f32_e32 v111, 0xbfb8aa3b, v111
	v_mul_f32_e32 v112, 0xbfb8aa3b, v112
	v_mul_f32_e32 v113, 0xbfb8aa3b, v113
	v_mul_f32_e32 v114, 0xbfb8aa3b, v114
	v_mul_f32_e32 v115, 0xbfb8aa3b, v115
	v_exp_f32_e32 v108, v108
	v_exp_f32_e32 v109, v109
	v_exp_f32_e32 v110, v110
	v_exp_f32_e32 v111, v111
	v_exp_f32_e32 v112, v112
	v_exp_f32_e32 v113, v113
	v_exp_f32_e32 v114, v114
	v_exp_f32_e32 v115, v115
	v_add_f32_e32 v108, 1.0, v108
	v_add_f32_e32 v109, 1.0, v109
	v_add_f32_e32 v110, 1.0, v110
	v_add_f32_e32 v111, 1.0, v111
	v_add_f32_e32 v112, 1.0, v112
	v_add_f32_e32 v113, 1.0, v113
	v_add_f32_e32 v114, 1.0, v114
	v_add_f32_e32 v115, 1.0, v115
	v_rcp_f32_e32 v108, v108
	v_rcp_f32_e32 v109, v109
	v_rcp_f32_e32 v110, v110
	v_rcp_f32_e32 v111, v111
	v_rcp_f32_e32 v112, v112
	v_rcp_f32_e32 v113, v113
	v_rcp_f32_e32 v114, v114
	v_rcp_f32_e32 v115, v115
	v_mul_f32_e32 v108, 0xbf60028b, v108
	v_mul_f32_e32 v109, 0xbf60028b, v109
	v_mul_f32_e32 v110, 0xbf60028b, v110
	v_mul_f32_e32 v111, 0xbf60028b, v111
	v_cvt_pk_bf16_f32 v116, v112, v113
	v_cvt_pk_bf16_f32 v117, v114, v115
	v_exp_f32_e32 v108, v108
	v_exp_f32_e32 v109, v109
	v_exp_f32_e32 v110, v110
	v_exp_f32_e32 v111, v111
	v_cvt_pk_bf16_f32 v118, v104, v105
	v_cvt_pk_bf16_f32 v119, v106, v107
	global_store_dwordx2 v136, v[116:117], s[44:45]
	global_store_dwordx2 v136, v[118:119], s[46:47]
	global_store_dwordx4 v135, v[108:111], s[54:55]
	v_add_u32_e32 v136, 32, v136
	v_add_u32_e32 v135, 64, v135
	s_lshl_b32 s2, s38, 2
	s_add_i32 s26, s26, s2
	s_branch .Llora_item
; __device__ __forceinline__ unsigned xb_ld(unsigned* p)              { return __hip_atomic_load(p, __ATOMIC_RELAXED, __HIP_MEMORY_SCOPE_AGENT); }
; __device__ __forceinline__ unsigned xb_add(unsigned* p, unsigned v) { return __hip_atomic_fetch_add(p, v, __ATOMIC_RELAXED, __HIP_MEMORY_SCOPE_AGENT); }
; __device__ __forceinline__ void xcd_barrier_complete(unsigned* bar, unsigned x, unsigned& nloc, unsigned& nx) {
;     const unsigned G = gridDim.x * gridDim.y * gridDim.z;
;     unsigned sum, cnt, mine, sp = 0u;
;     for (;;) {
;         sum = 0u; cnt = 0u; mine = 0u;
; #pragma unroll
;         for (unsigned j = 0; j < 16; ++j) { const unsigned c = xb_ld(&bar[XB_XCNT(j)]); sum += c; cnt += (c > 0u) ? 1u : 0u; mine = (j == x) ? c : mine; }
; __device__ __forceinline__ void xcd_barrier(const XcdBarrier& b) {
;     asm volatile("s_waitcnt vmcnt(0)" ::: "memory");
;     __syncthreads();
;     if (threadIdx.x == 0) {
;         unsigned* bar = b.bar;
;         __builtin_amdgcn_s_waitcnt(0);
;         unsigned nloc = b.st[0], nx = b.st[1];
;         if (nloc == 0u) { xcd_barrier_complete(bar, b.x, nloc, nx); b.st[0] = nloc; b.st[1] = nx; }
;         const unsigned old = xb_add(&bar[XB_XSUB(b.x)], 1u);
;         const unsigned gen = old / nloc;
.Llora_done:
.LBB0_1564:
	s_cmp_gt_i32 s37, 6
	s_cselect_b64 s[2:3], -1, 0
	s_and_b64 s[4:5], s[10:11], s[2:3]
	s_andn2_b64 vcc, exec, s[4:5]
	s_cbranch_vccnz .LBB0_1618
	s_waitcnt vmcnt(0)
	v_readlane_b32 s0, v238, 0
	v_readlane_b32 s1, v238, 1
	s_waitcnt vmcnt(0) lgkmcnt(0)
	s_barrier
	s_and_saveexec_b64 s[4:5], s[0:1]
	s_cbranch_execz .LBB0_1617
	s_add_i32 s6, 0, 0x23800
	v_mov_b32_e32 v0, s6
	s_waitcnt vmcnt(0) expcnt(0) lgkmcnt(0)
	ds_read_b32 v2, v0
	s_add_i32 s6, 0, 0x23804
	v_mov_b32_e32 v0, s6
	ds_read_b32 v0, v0
	s_waitcnt lgkmcnt(1)
	v_cmp_ne_u32_e32 vcc, 0, v2
	s_cbranch_vccnz .LBB0_1581
	s_add_u32 s6, s30, 0x3181200
	s_addc_u32 s7, s31, 0
	s_add_u32 s8, s30, 0x3181400
	s_addc_u32 s9, s31, 0
	s_add_u32 s10, s30, 0x3181500
	s_addc_u32 s11, s31, 0
	s_add_u32 s12, s30, 0x3181600
	s_addc_u32 s13, s31, 0
	s_add_u32 s14, s30, 0x3181700
	s_addc_u32 s15, s31, 0
	s_add_u32 s16, s30, 0x3181800
	s_addc_u32 s17, s31, 0
	s_add_u32 s18, s30, 0x3181900
	s_addc_u32 s19, s31, 0
	s_add_u32 s20, s30, 0x3181a00
	s_addc_u32 s21, s31, 0
	s_add_u32 s22, s30, 0x3181b00
	s_addc_u32 s23, s31, 0
	s_add_u32 s24, s30, 0x3181c00
	s_addc_u32 s25, s31, 0
	s_add_u32 s26, s30, 0x3181d00
	s_addc_u32 s27, s31, 0
	s_add_u32 s40, s30, 0x3181e00
	s_addc_u32 s41, s31, 0
	s_add_u32 s42, s30, 0x3181f00
	s_addc_u32 s43, s31, 0
	s_add_u32 s44, s30, 0x3182000
	s_addc_u32 s45, s31, 0
	s_add_u32 s46, s30, 0x3182100
	s_addc_u32 s47, s31, 0
	s_add_u32 s48, s30, 0x3182200
	s_addc_u32 s49, s31, 0
	s_mul_i32 s33, s39, s73
	s_add_u32 s50, s30, 0x3182300
	s_mul_i32 s33, s33, s38
	s_addc_u32 s51, s31, 0
	s_mov_b32 s34, 1
	v_mov_b32_e32 v16, 0
	s_branch .LBB0_1569
